# attention merged waits + no setprio; relaxed GEMM vmcnt ladders; batched gla_stage q/k/v staging loads
# speedup vs baseline: 1.3447x; 1.0074x over previous
.LBB0_201:
	s_and_b64 vcc, exec, s[0:1]
	s_cbranch_vccz .LBB0_192
	s_lshl_b32 s1, s11, 8
	v_add_u32_e32 v0, s1, v234
	v_ashrrev_i32_e32 v1, 31, v0
	s_lshl_b32 s0, s14, 7
	v_lshlrev_b64 v[0:1], 11, v[0:1]
	v_lshl_add_u64 v[194:195], v[178:179], 0, v[0:1]
	v_add_u32_e32 v0, s0, v234
	v_ashrrev_i32_e32 v1, 31, v0
	v_lshlrev_b64 v[0:1], 11, v[0:1]
	v_lshl_add_u64 v[196:197], v[180:181], 0, v[0:1]
	v_add_co_u32_e32 v0, vcc, 0x20000, v194
	s_mov_b64 s[6:7], 0x40000
	s_nop 0
	v_addc_co_u32_e32 v1, vcc, 0, v195, vcc
	v_add_co_u32_e32 v2, vcc, 0x40000, v194
	s_mov_b64 s[4:5], 0x20000
	s_nop 0
	v_addc_co_u32_e32 v3, vcc, 0, v195, vcc
	global_load_dwordx4 v[112:115], v[0:1], off
	global_load_dwordx4 v[116:119], v[2:3], off
	v_add_co_u32_e32 v0, vcc, 0x60000, v194
	global_load_dwordx4 v[120:123], v[194:195], off
	global_load_dwordx4 v[124:127], v[196:197], off
	v_addc_co_u32_e32 v1, vcc, 0, v195, vcc
	v_add_co_u32_e32 v2, vcc, 0x20000, v196
	v_lshl_add_u64 v[200:201], v[194:195], 0, s[6:7]
	s_nop 0
	v_addc_co_u32_e32 v3, vcc, 0, v197, vcc
	global_load_dwordx4 v[130:133], v[0:1], off
	global_load_dwordx4 v[134:137], v[2:3], off
	s_mov_b64 s[6:7], 0x60000
	v_lshl_add_u64 v[198:199], v[194:195], 0, s[4:5]
	v_lshl_add_u64 v[202:203], v[194:195], 0, s[6:7]
	v_lshl_add_u64 v[204:205], v[196:197], 0, s[4:5]
	s_and_saveexec_b64 s[4:5], s[2:3]
	s_xor_b64 s[4:5], exec, s[4:5]
	s_cbranch_execz .LBB0_208
	v_add_co_u32_e32 v0, vcc, 0x20000, v194
	s_mov_b32 s8, 0
	s_nop 0
	v_addc_co_u32_e32 v1, vcc, 0, v195, vcc
	v_add_co_u32_e32 v2, vcc, 0x40000, v194
	s_nop 1
	v_addc_co_u32_e32 v3, vcc, 0, v195, vcc
	v_add_co_u32_e32 v4, vcc, 0x60000, v194
	s_nop 1
	v_addc_co_u32_e32 v5, vcc, 0, v195, vcc
	v_add_co_u32_e32 v6, vcc, s58, v196
	s_nop 1
	v_addc_co_u32_e32 v7, vcc, 0, v197, vcc
	global_load_dwordx4 v[64:67], v[194:195], off offset:128
	global_load_dwordx4 v[68:71], v[0:1], off offset:128
	global_load_dwordx4 v[80:83], v[2:3], off offset:128
	global_load_dwordx4 v[84:87], v[4:5], off offset:128
	global_load_dwordx4 v[96:99], v[196:197], off offset:128
	global_load_dwordx4 v[100:103], v[6:7], off offset:128
	global_load_dwordx4 v[72:75], v[194:195], off offset:256
	global_load_dwordx4 v[76:79], v[0:1], off offset:256
	global_load_dwordx4 v[88:91], v[2:3], off offset:256
	global_load_dwordx4 v[92:95], v[4:5], off offset:256
	global_load_dwordx4 v[104:107], v[196:197], off offset:256
	global_load_dwordx4 v[108:111], v[6:7], off offset:256
	v_mov_b32_e32 v0, 0
	v_mov_b32_e32 v1, v0
	v_mov_b32_e32 v2, v0
	v_mov_b32_e32 v3, v0
	v_mov_b32_e32 v4, v0
	v_mov_b32_e32 v5, v0
	v_mov_b32_e32 v6, v0
	v_mov_b32_e32 v7, v0
	v_mov_b32_e32 v8, v0
	v_mov_b32_e32 v9, v0
	v_mov_b32_e32 v10, v0
	v_mov_b32_e32 v11, v0
	v_mov_b32_e32 v12, v0
	v_mov_b32_e32 v13, v0
	v_mov_b32_e32 v14, v0
	v_mov_b32_e32 v15, v0
	v_mov_b32_e32 v16, v0
	v_mov_b32_e32 v17, v0
	v_mov_b32_e32 v18, v0
	v_mov_b32_e32 v19, v0
	v_mov_b32_e32 v20, v0
	v_mov_b32_e32 v21, v0
	v_mov_b32_e32 v22, v0
	v_mov_b32_e32 v23, v0
	v_mov_b32_e32 v24, v0
	v_mov_b32_e32 v25, v0
	v_mov_b32_e32 v26, v0
	v_mov_b32_e32 v27, v0
	v_mov_b32_e32 v28, v0
	v_mov_b32_e32 v29, v0
	v_mov_b32_e32 v30, v0
	v_mov_b32_e32 v31, v0
	v_mov_b32_e32 v32, v0
	v_mov_b32_e32 v33, v0
	v_mov_b32_e32 v34, v0
	v_mov_b32_e32 v35, v0
	v_mov_b32_e32 v36, v0
	v_mov_b32_e32 v37, v0
	v_mov_b32_e32 v38, v0
	v_mov_b32_e32 v39, v0
	v_mov_b32_e32 v40, v0
	v_mov_b32_e32 v41, v0
	v_mov_b32_e32 v42, v0
	v_mov_b32_e32 v43, v0
	v_mov_b32_e32 v44, v0
	v_mov_b32_e32 v45, v0
	v_mov_b32_e32 v46, v0
	v_mov_b32_e32 v47, v0
	v_mov_b32_e32 v48, v0
	v_mov_b32_e32 v49, v0
	v_mov_b32_e32 v50, v0
	v_mov_b32_e32 v51, v0
	v_mov_b32_e32 v52, v0
	v_mov_b32_e32 v53, v0
	v_mov_b32_e32 v54, v0
	v_mov_b32_e32 v55, v0
	v_mov_b32_e32 v56, v0
	v_mov_b32_e32 v57, v0
	v_mov_b32_e32 v58, v0
	v_mov_b32_e32 v59, v0
	v_mov_b32_e32 v60, v0
	v_mov_b32_e32 v61, v0
	v_mov_b32_e32 v62, v0
	v_mov_b32_e32 v63, v0
	s_waitcnt vmcnt(15)
	ds_write_b128 v235, v[120:123]
	ds_write_b128 v235, v[112:115] offset:9216
	ds_write_b128 v235, v[116:119] offset:18432
	s_waitcnt vmcnt(13)
	ds_write_b128 v235, v[130:133] offset:27648
	ds_write_b128 v235, v[124:127] offset:36864
	s_waitcnt vmcnt(12)
	ds_write_b128 v235, v[134:137] offset:46080
	s_waitcnt lgkmcnt(0)
	s_barrier
	s_branch .LBB0_205
.LBB0_204:
	s_min_u32 s9, s8, 11
	s_lshl_b32 s48, s9, 7
	s_add_i32 s16, s48, 0x200
	s_mov_b32 s17, s49
	s_waitcnt vmcnt(6)
	v_lshl_add_u64 v[72:73], v[194:195], 0, s[48:49]
	v_lshl_add_u64 v[76:77], v[198:199], 0, s[16:17]
	v_lshl_add_u64 v[88:89], v[200:201], 0, s[16:17]
	v_lshl_add_u64 v[92:93], v[202:203], 0, s[16:17]
	v_lshl_add_u64 v[104:105], v[196:197], 0, s[48:49]
	v_lshl_add_u64 v[108:109], v[204:205], 0, s[16:17]
	global_load_dwordx4 v[72:75], v[72:73], off offset:512
	s_nop 0
	global_load_dwordx4 v[76:79], v[76:77], off
	s_nop 0
	global_load_dwordx4 v[88:91], v[88:89], off
	s_nop 0
	global_load_dwordx4 v[92:95], v[92:93], off
	s_nop 0
	global_load_dwordx4 v[104:107], v[104:105], off offset:512
	s_nop 0
	global_load_dwordx4 v[108:111], v[108:109], off
	s_add_i32 s8, s8, 2
	s_waitcnt lgkmcnt(0)
	s_barrier
	v_mfma_f32_32x32x16_bf16 v[48:63], v[162:165], v[170:173], v[48:63]
	v_mfma_f32_32x32x16_bf16 v[32:47], v[162:165], v[174:177], v[32:47]
	v_mfma_f32_32x32x16_bf16 v[16:31], v[166:169], v[170:173], v[16:31]
	v_mfma_f32_32x32x16_bf16 v[0:15], v[166:169], v[174:177], v[0:15]
	v_mfma_f32_32x32x16_bf16 v[48:63], v[130:133], v[134:137], v[48:63]
	v_mfma_f32_32x32x16_bf16 v[32:47], v[130:133], v[150:153], v[32:47]
	v_mfma_f32_32x32x16_bf16 v[16:31], v[142:145], v[134:137], v[16:31]
	v_mfma_f32_32x32x16_bf16 v[0:15], v[142:145], v[150:153], v[0:15]
	v_mfma_f32_32x32x16_bf16 v[48:63], v[138:141], v[154:157], v[48:63]
	v_mfma_f32_32x32x16_bf16 v[32:47], v[138:141], v[158:161], v[32:47]
	v_mfma_f32_32x32x16_bf16 v[16:31], v[146:149], v[154:157], v[16:31]
	v_mfma_f32_32x32x16_bf16 v[0:15], v[146:149], v[158:161], v[0:15]
	v_mfma_f32_32x32x16_bf16 v[48:63], v[116:119], v[120:123], v[48:63]
	v_mfma_f32_32x32x16_bf16 v[32:47], v[116:119], v[124:127], v[32:47]
	v_mfma_f32_32x32x16_bf16 v[16:31], v[112:115], v[120:123], v[16:31]
	v_mfma_f32_32x32x16_bf16 v[0:15], v[112:115], v[124:127], v[0:15]
	s_andn2_b64 vcc, exec, s[6:7]
	s_barrier
	s_cbranch_vccz .LBB0_207
.LBB0_205:
	ds_read_b128 v[112:115], v237
	ds_read_b128 v[116:119], v237 offset:32
	ds_read_b128 v[120:123], v237 offset:4608
	ds_read_b128 v[124:127], v237 offset:4640
	ds_read_b128 v[130:133], v238 offset:36864
	ds_read_b128 v[134:137], v238 offset:36896
	ds_read_b128 v[138:141], v238 offset:41472
	ds_read_b128 v[142:145], v238 offset:41504
	ds_read_b128 v[146:149], v237 offset:64
	ds_read_b128 v[150:153], v237 offset:96
	ds_read_b128 v[154:157], v237 offset:4672
	ds_read_b128 v[158:161], v237 offset:4704
	ds_read_b128 v[162:165], v238 offset:36928
	ds_read_b128 v[166:169], v238 offset:36960
	ds_read_b128 v[170:173], v238 offset:41536
	ds_read_b128 v[174:177], v238 offset:41568
	s_min_u32 s6, s8, 12
	s_lshl_b32 s48, s6, 7
	s_add_i32 s6, s48, 0x180
	s_mov_b32 s7, s49
	s_waitcnt vmcnt(11)
	ds_write_b128 v235, v[64:67] offset:55296
	s_waitcnt vmcnt(10)
	ds_write_b128 v235, v[68:71] offset:64512
	s_waitcnt vmcnt(9)
	ds_write_b128 v239, v[80:83] offset:18432
	s_waitcnt vmcnt(8)
	ds_write_b128 v239, v[84:87] offset:27648
	s_waitcnt vmcnt(7)
	ds_write_b128 v240, v[96:99]
	s_waitcnt vmcnt(6)
	ds_write_b128 v240, v[100:103] offset:9216
	v_lshl_add_u64 v[64:65], v[194:195], 0, s[48:49]
	v_lshl_add_u64 v[68:69], v[198:199], 0, s[6:7]
	v_lshl_add_u64 v[80:81], v[200:201], 0, s[6:7]
	v_lshl_add_u64 v[84:85], v[202:203], 0, s[6:7]
	v_lshl_add_u64 v[96:97], v[196:197], 0, s[48:49]
	v_lshl_add_u64 v[100:101], v[204:205], 0, s[6:7]
	global_load_dwordx4 v[64:67], v[64:65], off offset:384
	s_nop 0
	global_load_dwordx4 v[68:71], v[68:69], off
	s_nop 0
	global_load_dwordx4 v[80:83], v[80:81], off
	s_nop 0
	global_load_dwordx4 v[84:87], v[84:85], off
	s_nop 0
	global_load_dwordx4 v[96:99], v[96:97], off offset:384
	s_nop 0
	global_load_dwordx4 v[100:103], v[100:101], off
	s_waitcnt lgkmcnt(0)
	s_barrier
	v_mfma_f32_32x32x16_bf16 v[48:63], v[112:115], v[130:133], v[48:63]
	v_mfma_f32_32x32x16_bf16 v[32:47], v[112:115], v[138:141], v[32:47]
	v_mfma_f32_32x32x16_bf16 v[16:31], v[120:123], v[130:133], v[16:31]
	v_mfma_f32_32x32x16_bf16 v[0:15], v[120:123], v[138:141], v[0:15]
	v_mfma_f32_32x32x16_bf16 v[48:63], v[116:119], v[134:137], v[48:63]
	v_mfma_f32_32x32x16_bf16 v[32:47], v[116:119], v[142:145], v[32:47]
	v_mfma_f32_32x32x16_bf16 v[16:31], v[124:127], v[134:137], v[16:31]
	v_mfma_f32_32x32x16_bf16 v[0:15], v[124:127], v[142:145], v[0:15]
	v_mfma_f32_32x32x16_bf16 v[48:63], v[146:149], v[162:165], v[48:63]
	v_mfma_f32_32x32x16_bf16 v[32:47], v[146:149], v[170:173], v[32:47]
	v_mfma_f32_32x32x16_bf16 v[16:31], v[154:157], v[162:165], v[16:31]
	v_mfma_f32_32x32x16_bf16 v[0:15], v[154:157], v[170:173], v[0:15]
	v_mfma_f32_32x32x16_bf16 v[48:63], v[150:153], v[166:169], v[48:63]
	v_mfma_f32_32x32x16_bf16 v[32:47], v[150:153], v[174:177], v[32:47]
	v_mfma_f32_32x32x16_bf16 v[16:31], v[158:161], v[166:169], v[16:31]
	v_mfma_f32_32x32x16_bf16 v[0:15], v[158:161], v[174:177], v[0:15]
	s_barrier
	ds_read_b128 v[162:165], v237 offset:55296
	ds_read_b128 v[130:133], v237 offset:55328
	ds_read_b128 v[170:173], v241
	ds_read_b128 v[134:137], v241 offset:32
	ds_read_b128 v[166:169], v237 offset:59904
	ds_read_b128 v[142:145], v237 offset:59936
	ds_read_b128 v[174:177], v241 offset:4608
	ds_read_b128 v[150:153], v241 offset:4640
	ds_read_b128 v[138:141], v237 offset:55360
	ds_read_b128 v[116:119], v237 offset:55392
	ds_read_b128 v[146:149], v237 offset:59968
	ds_read_b128 v[112:115], v237 offset:60000
	ds_read_b128 v[154:157], v241 offset:64
	ds_read_b128 v[120:123], v241 offset:96
	ds_read_b128 v[158:161], v241 offset:4672
	ds_read_b128 v[124:127], v241 offset:4704
	s_cmp_gt_u32 s8, 13
	s_cselect_b64 s[6:7], -1, 0
	s_and_b64 vcc, exec, s[6:7]
	s_cbranch_vccnz .LBB0_204
	s_waitcnt vmcnt(11)
	ds_write_b128 v235, v[72:75]
	s_waitcnt vmcnt(10)
	ds_write_b128 v235, v[76:79] offset:9216
	s_waitcnt vmcnt(9)
	ds_write_b128 v235, v[88:91] offset:18432
	s_waitcnt vmcnt(8)
	ds_write_b128 v235, v[92:95] offset:27648
	s_waitcnt vmcnt(7)
	ds_write_b128 v235, v[104:107] offset:36864
	s_waitcnt vmcnt(6)
	ds_write_b128 v235, v[108:111] offset:46080
	s_branch .LBB0_204
.LBB0_207:
.LBB0_208:
	s_andn2_saveexec_b64 s[4:5], s[4:5]
	s_cbranch_execz .LBB0_191
	s_nop 5
	v_add_co_u32_e32 v24, vcc, 0x20000, v194
	global_load_dwordx4 v[0:3], v[194:195], off offset:128
	s_nop 0
	v_addc_co_u32_e32 v25, vcc, 0, v195, vcc
	v_add_co_u32_e32 v26, vcc, 0x40000, v194
	global_load_dwordx4 v[4:7], v[24:25], off offset:128
	s_nop 0
	v_addc_co_u32_e32 v27, vcc, 0, v195, vcc
	v_add_co_u32_e32 v28, vcc, 0x60000, v194
	global_load_dwordx4 v[8:11], v[26:27], off offset:128
	s_nop 0
	v_addc_co_u32_e32 v29, vcc, 0, v195, vcc
	global_load_dwordx4 v[12:15], v[28:29], off offset:128
	global_load_dwordx4 v[16:19], v[196:197], off offset:128
	v_add_co_u32_e32 v30, vcc, s58, v196
	s_mov_b32 s15, 0
	s_nop 0
	v_addc_co_u32_e32 v31, vcc, 0, v197, vcc
	global_load_dwordx4 v[20:23], v[30:31], off offset:128
	global_load_dwordx4 v[64:67], v[194:195], off offset:256
	global_load_dwordx4 v[68:71], v[24:25], off offset:256
	global_load_dwordx4 v[72:75], v[28:29], off offset:256
	global_load_dwordx4 v[84:87], v[26:27], off offset:256
	global_load_dwordx4 v[96:99], v[196:197], off offset:256
	global_load_dwordx4 v[100:103], v[30:31], off offset:256
	global_load_dwordx4 v[76:79], v[194:195], off offset:384
	global_load_dwordx4 v[80:83], v[24:25], off offset:384
	global_load_dwordx4 v[88:91], v[26:27], off offset:384
	global_load_dwordx4 v[92:95], v[28:29], off offset:384
	global_load_dwordx4 v[104:107], v[196:197], off offset:384
	global_load_dwordx4 v[108:111], v[30:31], off offset:384
	s_waitcnt vmcnt(21)
	ds_write_b128 v235, v[120:123]
	ds_write_b128 v235, v[112:115] offset:9216
	ds_write_b128 v235, v[116:119] offset:18432
	s_waitcnt vmcnt(19)
	ds_write_b128 v235, v[130:133] offset:27648
	ds_write_b128 v235, v[124:127] offset:36864
	s_waitcnt vmcnt(18)
	ds_write_b128 v235, v[134:137] offset:46080
	s_waitcnt vmcnt(17)
	ds_write_b128 v235, v[0:3] offset:55296
	s_waitcnt vmcnt(13)
	ds_write_b128 v240, v[16:19]
	ds_write_b128 v235, v[4:7] offset:64512
	ds_write_b128 v239, v[8:11] offset:18432
	ds_write_b128 v239, v[12:15] offset:27648
	s_waitcnt vmcnt(12)
	ds_write_b128 v240, v[20:23] offset:9216
	s_waitcnt lgkmcnt(0)
	s_barrier
	ds_read_b128 v[116:119], v237
	ds_read_b128 v[112:115], v237 offset:32
	ds_read_b128 v[124:127], v238 offset:36864
	ds_read_b128 v[120:123], v238 offset:36896
	ds_read_b128 v[134:137], v237 offset:4608
	ds_read_b128 v[130:133], v237 offset:4640
	ds_read_b128 v[154:157], v238 offset:41472
	ds_read_b128 v[142:145], v238 offset:41504
	ds_read_b128 v[138:141], v237 offset:64
	ds_read_b128 v[146:149], v237 offset:96
	ds_read_b128 v[158:161], v237 offset:4672
	ds_read_b128 v[150:153], v237 offset:4704
	ds_read_b128 v[170:173], v238 offset:36928
	ds_read_b128 v[162:165], v238 offset:36960
	ds_read_b128 v[174:177], v238 offset:41536
	ds_read_b128 v[166:169], v238 offset:41568
	v_mov_b32_e32 v0, 0
	v_mov_b32_e32 v1, v0
	v_mov_b32_e32 v2, v0
	v_mov_b32_e32 v3, v0
	v_mov_b32_e32 v4, v0
	v_mov_b32_e32 v5, v0
	v_mov_b32_e32 v6, v0
	v_mov_b32_e32 v7, v0
	v_mov_b32_e32 v8, v0
	v_mov_b32_e32 v9, v0
	v_mov_b32_e32 v10, v0
	v_mov_b32_e32 v11, v0
	v_mov_b32_e32 v12, v0
	v_mov_b32_e32 v13, v0
	v_mov_b32_e32 v14, v0
	v_mov_b32_e32 v15, v0
	v_mov_b32_e32 v16, v0
	v_mov_b32_e32 v17, v0
	v_mov_b32_e32 v18, v0
	v_mov_b32_e32 v19, v0
	v_mov_b32_e32 v20, v0
	v_mov_b32_e32 v21, v0
	v_mov_b32_e32 v22, v0
	v_mov_b32_e32 v23, v0
	v_mov_b32_e32 v24, v0
	v_mov_b32_e32 v25, v0
	v_mov_b32_e32 v26, v0
	v_mov_b32_e32 v27, v0
	v_mov_b32_e32 v28, v0
	v_mov_b32_e32 v29, v0
	v_mov_b32_e32 v30, v0
	v_mov_b32_e32 v31, v0
	v_mov_b32_e32 v32, v0
	v_mov_b32_e32 v33, v0
	v_mov_b32_e32 v34, v0
	v_mov_b32_e32 v35, v0
	v_mov_b32_e32 v36, v0
	v_mov_b32_e32 v37, v0
	v_mov_b32_e32 v38, v0
	v_mov_b32_e32 v39, v0
	v_mov_b32_e32 v40, v0
	v_mov_b32_e32 v41, v0
	v_mov_b32_e32 v42, v0
	v_mov_b32_e32 v43, v0
	v_mov_b32_e32 v44, v0
	v_mov_b32_e32 v45, v0
	v_mov_b32_e32 v46, v0
	v_mov_b32_e32 v47, v0
	v_mov_b32_e32 v48, v0
	v_mov_b32_e32 v49, v0
	v_mov_b32_e32 v50, v0
	v_mov_b32_e32 v51, v0
	v_mov_b32_e32 v52, v0
	v_mov_b32_e32 v53, v0
	v_mov_b32_e32 v54, v0
	v_mov_b32_e32 v55, v0
	v_mov_b32_e32 v56, v0
	v_mov_b32_e32 v57, v0
	v_mov_b32_e32 v58, v0
	v_mov_b32_e32 v59, v0
	v_mov_b32_e32 v60, v0
	v_mov_b32_e32 v61, v0
	v_mov_b32_e32 v62, v0
	v_mov_b32_e32 v63, v0
	s_branch .LBB0_211
.LBB0_210:
	s_min_u32 s8, s15, 10
	s_lshl_b32 s48, s8, 7
	s_add_i32 s8, s48, 0x280
	s_mov_b32 s9, s49
	s_waitcnt vmcnt(6)
	v_lshl_add_u64 v[76:77], v[194:195], 0, s[48:49]
	v_lshl_add_u64 v[80:81], v[198:199], 0, s[8:9]
	v_lshl_add_u64 v[88:89], v[200:201], 0, s[8:9]
	v_lshl_add_u64 v[92:93], v[202:203], 0, s[8:9]
	v_lshl_add_u64 v[104:105], v[196:197], 0, s[48:49]
	v_lshl_add_u64 v[108:109], v[204:205], 0, s[8:9]
	global_load_dwordx4 v[76:79], v[76:77], off offset:640
	s_nop 0
	global_load_dwordx4 v[80:83], v[80:81], off
	s_nop 0
	global_load_dwordx4 v[88:91], v[88:89], off
	s_nop 0
	global_load_dwordx4 v[92:95], v[92:93], off
	s_nop 0
	global_load_dwordx4 v[104:107], v[104:105], off offset:640
	s_nop 0
	global_load_dwordx4 v[108:111], v[108:109], off
	s_add_i32 s15, s15, 2
	s_and_b64 vcc, exec, s[6:7]
	s_waitcnt lgkmcnt(0)
	s_barrier
	s_cbranch_vccnz .LBB0_191
.LBB0_211:
	s_waitcnt lgkmcnt(13)
	v_mfma_f32_32x32x16_bf16 v[48:63], v[116:119], v[124:127], v[48:63]
	s_waitcnt lgkmcnt(9)
	v_mfma_f32_32x32x16_bf16 v[32:47], v[116:119], v[154:157], v[32:47]
	v_mfma_f32_32x32x16_bf16 v[16:31], v[134:137], v[124:127], v[16:31]
	v_mfma_f32_32x32x16_bf16 v[0:15], v[134:137], v[154:157], v[0:15]
	v_mfma_f32_32x32x16_bf16 v[48:63], v[112:115], v[120:123], v[48:63]
	s_waitcnt lgkmcnt(8)
	v_mfma_f32_32x32x16_bf16 v[32:47], v[112:115], v[142:145], v[32:47]
	v_mfma_f32_32x32x16_bf16 v[16:31], v[130:133], v[120:123], v[16:31]
	v_mfma_f32_32x32x16_bf16 v[0:15], v[130:133], v[142:145], v[0:15]
	s_waitcnt lgkmcnt(3)
	v_mfma_f32_32x32x16_bf16 v[48:63], v[138:141], v[170:173], v[48:63]
	s_waitcnt lgkmcnt(1)
	v_mfma_f32_32x32x16_bf16 v[32:47], v[138:141], v[174:177], v[32:47]
	v_mfma_f32_32x32x16_bf16 v[16:31], v[158:161], v[170:173], v[16:31]
	v_mfma_f32_32x32x16_bf16 v[0:15], v[158:161], v[174:177], v[0:15]
	v_mfma_f32_32x32x16_bf16 v[48:63], v[146:149], v[162:165], v[48:63]
	s_waitcnt lgkmcnt(0)
	v_mfma_f32_32x32x16_bf16 v[32:47], v[146:149], v[166:169], v[32:47]
	v_mfma_f32_32x32x16_bf16 v[16:31], v[150:153], v[162:165], v[16:31]
	v_mfma_f32_32x32x16_bf16 v[0:15], v[150:153], v[166:169], v[0:15]
	s_barrier
	ds_read_b128 v[116:119], v237 offset:55296
	ds_read_b128 v[112:115], v237 offset:55328
	ds_read_b128 v[124:127], v241
	ds_read_b128 v[120:123], v241 offset:32
	ds_read_b128 v[134:137], v237 offset:59904
	ds_read_b128 v[130:133], v237 offset:59936
	ds_read_b128 v[154:157], v241 offset:4608
	ds_read_b128 v[142:145], v241 offset:4640
	ds_read_b128 v[138:141], v237 offset:55360
	ds_read_b128 v[146:149], v237 offset:55392
	ds_read_b128 v[158:161], v237 offset:59968
	ds_read_b128 v[150:153], v237 offset:60000
	ds_read_b128 v[170:173], v241 offset:64
	ds_read_b128 v[162:165], v241 offset:96
	ds_read_b128 v[174:177], v241 offset:4672
	ds_read_b128 v[166:169], v241 offset:4704
	s_cmp_lt_u32 s15, 14
	s_cselect_b64 s[8:9], -1, 0
	s_cmp_gt_u32 s15, 13
	s_cselect_b64 s[6:7], -1, 0
	s_and_b64 vcc, exec, s[6:7]
	s_cbranch_vccnz .LBB0_213
	s_waitcnt vmcnt(11)
	ds_write_b128 v235, v[64:67]
	s_waitcnt vmcnt(10)
	ds_write_b128 v235, v[68:71] offset:9216
	s_waitcnt vmcnt(8)
	ds_write_b128 v235, v[84:87] offset:18432
	ds_write_b128 v235, v[72:75] offset:27648
	s_waitcnt vmcnt(7)
	ds_write_b128 v235, v[96:99] offset:36864
	s_waitcnt vmcnt(6)
	ds_write_b128 v235, v[100:103] offset:46080
.LBB0_213:
	s_min_u32 s16, s15, 11
	s_lshl_b32 s48, s16, 7
	s_add_i32 s16, s48, 0x200
	s_mov_b32 s17, s49
	s_waitcnt vmcnt(6)
	v_lshl_add_u64 v[64:65], v[194:195], 0, s[48:49]
	v_lshl_add_u64 v[68:69], v[198:199], 0, s[16:17]
	v_lshl_add_u64 v[72:73], v[200:201], 0, s[16:17]
	v_lshl_add_u64 v[74:75], v[202:203], 0, s[16:17]
	v_lshl_add_u64 v[96:97], v[196:197], 0, s[48:49]
	v_lshl_add_u64 v[100:101], v[204:205], 0, s[16:17]
	global_load_dwordx4 v[64:67], v[64:65], off offset:512
	s_nop 0
	global_load_dwordx4 v[68:71], v[68:69], off
	s_nop 0
	global_load_dwordx4 v[84:87], v[72:73], off
	s_nop 0
	global_load_dwordx4 v[72:75], v[74:75], off
	s_nop 0
	global_load_dwordx4 v[96:99], v[96:97], off offset:512
	s_nop 0
	global_load_dwordx4 v[100:103], v[100:101], off
	s_waitcnt lgkmcnt(0)
	s_barrier
	v_mfma_f32_32x32x16_bf16 v[48:63], v[116:119], v[124:127], v[48:63]
	v_mfma_f32_32x32x16_bf16 v[32:47], v[116:119], v[154:157], v[32:47]
	v_mfma_f32_32x32x16_bf16 v[16:31], v[134:137], v[124:127], v[16:31]
	v_mfma_f32_32x32x16_bf16 v[0:15], v[134:137], v[154:157], v[0:15]
	v_mfma_f32_32x32x16_bf16 v[48:63], v[112:115], v[120:123], v[48:63]
	v_mfma_f32_32x32x16_bf16 v[32:47], v[112:115], v[142:145], v[32:47]
	v_mfma_f32_32x32x16_bf16 v[16:31], v[130:133], v[120:123], v[16:31]
	v_mfma_f32_32x32x16_bf16 v[0:15], v[130:133], v[142:145], v[0:15]
	v_mfma_f32_32x32x16_bf16 v[48:63], v[138:141], v[170:173], v[48:63]
	v_mfma_f32_32x32x16_bf16 v[32:47], v[138:141], v[174:177], v[32:47]
	v_mfma_f32_32x32x16_bf16 v[16:31], v[158:161], v[170:173], v[16:31]
	v_mfma_f32_32x32x16_bf16 v[0:15], v[158:161], v[174:177], v[0:15]
	v_mfma_f32_32x32x16_bf16 v[48:63], v[146:149], v[162:165], v[48:63]
	v_mfma_f32_32x32x16_bf16 v[32:47], v[146:149], v[166:169], v[32:47]
	v_mfma_f32_32x32x16_bf16 v[16:31], v[150:153], v[162:165], v[16:31]
	v_mfma_f32_32x32x16_bf16 v[0:15], v[150:153], v[166:169], v[0:15]
	s_andn2_b64 vcc, exec, s[8:9]
	s_barrier
	s_cbranch_vccnz .LBB0_215
	ds_read_b128 v[116:119], v237
	ds_read_b128 v[112:115], v237 offset:32
	ds_read_b128 v[124:127], v238 offset:36864
	ds_read_b128 v[120:123], v238 offset:36896
	ds_read_b128 v[134:137], v237 offset:4608
	ds_read_b128 v[130:133], v237 offset:4640
	ds_read_b128 v[154:157], v238 offset:41472
	ds_read_b128 v[142:145], v238 offset:41504
	ds_read_b128 v[138:141], v237 offset:64
	ds_read_b128 v[146:149], v237 offset:96
	ds_read_b128 v[158:161], v237 offset:4672
	ds_read_b128 v[150:153], v237 offset:4704
	ds_read_b128 v[170:173], v238 offset:36928
	ds_read_b128 v[162:165], v238 offset:36960
	ds_read_b128 v[174:177], v238 offset:41536
	ds_read_b128 v[166:169], v238 offset:41568
.LBB0_215:
	s_cmp_gt_u32 s15, 12
	s_cbranch_scc1 .LBB0_210
	s_waitcnt vmcnt(11)
	ds_write_b128 v235, v[76:79] offset:55296
	s_waitcnt vmcnt(10)
	ds_write_b128 v235, v[80:83] offset:64512
	s_waitcnt vmcnt(9)
	ds_write_b128 v239, v[88:91] offset:18432
	s_waitcnt vmcnt(8)
	ds_write_b128 v239, v[92:95] offset:27648
	s_waitcnt vmcnt(7)
	ds_write_b128 v240, v[104:107]
	s_waitcnt vmcnt(6)
	ds_write_b128 v240, v[108:111] offset:9216
	s_branch .LBB0_210

.LBB0_290:
	ds_read_b64 v[0:1], v129 offset:232
	s_movk_i32 s0, 0x400
	v_cmp_gt_i32_e32 vcc, s0, v64
	s_mov_b64 s[0:1], 0x3195000
	v_lshlrev_b32_e32 v2, 3, v64
	s_waitcnt lgkmcnt(0)
	v_lshl_add_u64 v[0:1], v[0:1], 0, s[0:1]
	v_ashrrev_i32_e32 v2, 4, v64
	v_and_b32_e32 v3, 15, v64
	v_lshlrev_b32_e32 v128, 4, v3
	v_add_u32_e32 v4, s4, v2
	v_mad_i64_i32 v[6:7], s[2:3], v4, s86, v[0:1]
	v_lshl_add_u64 v[6:7], v[6:7], 0, v[128:129]
	global_load_dwordx4 v[12:15], v[6:7], off
	global_load_dwordx4 v[16:19], v[6:7], off offset:256
	v_add_co_u32_e32 v8, vcc, 0x32000, v6
	s_nop 1
	v_addc_co_u32_e32 v9, vcc, 0, v7, vcc
	global_load_dwordx4 v[20:23], v[8:9], off
	global_load_dwordx4 v[24:27], v[8:9], off offset:256
	v_mul_lo_u32 v5, v2, s92
	v_add3_u32 v5, s57, v5, v128
	v_ashrrev_i32_e32 v10, 5, v64
	v_and_b32_e32 v11, 31, v64
	v_lshlrev_b32_e32 v128, 4, v11
	v_add_u32_e32 v4, s4, v10
	v_mad_i64_i32 v[6:7], s[2:3], v4, s86, v[0:1]
	v_lshl_add_u64 v[6:7], v[6:7], 0, v[128:129]
	global_load_dwordx4 v[28:31], v[6:7], off offset:512
	v_add_co_u32_e32 v6, vcc, 0x19000, v6
	s_nop 1
	v_addc_co_u32_e32 v7, vcc, 0, v7, vcc
	global_load_dwordx4 v[32:35], v[6:7], off offset:512
	v_add_co_u32_e32 v6, vcc, 0x19000, v6
	s_nop 1
	v_addc_co_u32_e32 v7, vcc, 0, v7, vcc
	global_load_dwordx4 v[36:39], v[6:7], off offset:512
	v_add_co_u32_e32 v6, vcc, 0x19000, v6
	s_nop 1
	v_addc_co_u32_e32 v7, vcc, 0, v7, vcc
	global_load_dwordx4 v[40:43], v[6:7], off offset:512
	v_lshlrev_b32_e32 v10, 9, v10
	v_add3_u32 v10, s57, v10, v128
	s_waitcnt vmcnt(7)
	ds_write_b128 v5, v[12:15]
	s_waitcnt vmcnt(6)
	ds_write_b128 v5, v[16:19] offset:17408
	s_waitcnt vmcnt(5)
	ds_write_b128 v5, v[20:23] offset:8704
	s_waitcnt vmcnt(4)
	ds_write_b128 v5, v[24:27] offset:26112
	s_waitcnt vmcnt(3)
	ds_write_b128 v10, v[28:31] offset:34816
	s_waitcnt vmcnt(2)
	ds_write_b128 v10, v[32:35] offset:43008
	s_waitcnt vmcnt(1)
	ds_write_b128 v10, v[36:39] offset:51200
	s_waitcnt vmcnt(0)
	ds_write_b128 v10, v[40:43] offset:59392
	v_ashrrev_i32_e32 v4, 3, v64
	v_and_b32_e32 v2, 7, v64
	v_add_u32_e32 v3, s4, v4
	v_mad_i64_i32 v[0:1], s[0:1], v3, s86, v[0:1]
	v_lshlrev_b32_e32 v128, 3, v2
	v_lshl_add_u64 v[0:1], v[0:1], 0, v[128:129]
	global_load_dwordx2 v[2:3], v[0:1], off offset:1024
	v_lshlrev_b32_e32 v0, 4, v64
	v_and_b32_e32 v1, 64, v0
	v_add_lshl_u32 v1, v1, v4, 6
	v_and_b32_e32 v0, 48, v0
	v_readlane_b32 s0, v255, 16
	v_and_b32_e32 v6, 0x7f, v64
	v_ashrrev_i32_e32 v14, 7, v64
	v_add3_u32 v4, s0, v1, v0
	v_or_b32_e32 v128, s9, v6
	s_movk_i32 s0, 0x204
	v_cmp_gt_i32_e64 s[2:3], 64, v14
	v_mul_lo_u32 v22, v14, s0
	v_lshlrev_b32_e32 v15, 2, v6
	v_add_u32_e32 v16, -4, v14
	v_lshlrev_b32_e32 v17, 6, v14
	s_waitcnt vmcnt(0)
	v_lshlrev_b32_e32 v0, 16, v2
	v_and_b32_e32 v1, 0xffff0000, v2
	v_lshlrev_b32_e32 v2, 16, v3
	v_and_b32_e32 v3, 0xffff0000, v3
	ds_write_b128 v4, v[0:3]
	s_waitcnt lgkmcnt(0)
	s_barrier
	ds_read2_b64 v[2:5], v129 offset0:9 offset1:10
	v_or_b32_e32 v0, s6, v6
	v_mov_b32_e32 v1, v129
	s_waitcnt lgkmcnt(0)
	v_lshl_add_u64 v[2:3], v[128:129], 2, v[2:3]
	v_lshl_add_u64 v[10:11], v[0:1], 2, v[4:5]
	s_and_saveexec_b64 s[0:1], s[2:3]
	s_cbranch_execz .LBB0_299
	v_add_co_u32_e32 v26, vcc, 0x1000, v2
	global_load_dword v18, v[2:3], off
	global_load_dword v19, v[2:3], off offset:512
	global_load_dword v20, v[2:3], off offset:1024
	global_load_dword v21, v[2:3], off offset:1536
	global_load_dword v23, v[2:3], off offset:2048
	global_load_dword v24, v[2:3], off offset:2560
	global_load_dword v0, v[2:3], off offset:3072
	global_load_dword v1, v[2:3], off offset:3584
	v_addc_co_u32_e32 v27, vcc, 0, v3, vcc
	global_load_dword v4, v[26:27], off
	global_load_dword v5, v[26:27], off offset:512
	global_load_dword v6, v[26:27], off offset:1024
	global_load_dword v7, v[26:27], off offset:1536
	global_load_dword v8, v[26:27], off offset:2048
	global_load_dword v9, v[26:27], off offset:2560
	global_load_dword v12, v[26:27], off offset:3072
	global_load_dword v13, v[26:27], off offset:3584
	global_load_dword v25, v[10:11], off
	s_mov_b32 s4, 0x10800
	v_add_u32_e32 v26, -4, v14
	v_add3_u32 v27, v22, v15, s4
	v_lshlrev_b32_e32 v28, 6, v14
	s_mov_b64 s[4:5], 0

.LBB0_605:
	s_lshl_b32 s0, s9, 5
	s_and_b32 s0, s0, 0xe0
	s_ashr_i32 s1, s9, 3
	s_add_i32 s2, s0, s1
	s_and_b64 s[0:1], s[72:73], exec
	s_cselect_b32 s0, s2, s9
	v_mov_b32_e32 v4, v206
	s_ashr_i32 s19, s0, 7
	ds_read_b64 v[0:1], v129 offset:232
	s_lshl_b32 s1, s0, 8
	s_bfe_u32 s18, s0, 0x20005
	s_lshl_b32 s2, s19, 2
	s_and_b32 s1, s1, 0x1f00
	v_and_b32_e32 v5, 31, v4
	s_or_b32 s0, s18, s2
	v_ashrrev_i32_e32 v2, 1, v4
	s_lshl_b32 s20, s0, 1
	v_and_b32_e32 v2, 0xffffffe0, v2
	v_or_b32_e32 v3, s1, v5
	v_bfe_u32 v6, v4, 5, 1
	s_mul_i32 s16, s0, 0x108000
	s_mul_hi_i32 s17, s20, 0x84000
	v_add_u32_e32 v156, v3, v2
	s_waitcnt lgkmcnt(0)
	v_lshl_add_u64 v[8:9], v[0:1], 0, s[16:17]
	v_ashrrev_i32_e32 v157, 31, v156
	v_lshlrev_b32_e32 v128, 4, v6
	v_lshl_add_u64 v[2:3], v[8:9], 0, v[128:129]
	v_lshlrev_b64 v[10:11], 6, v[156:157]
	v_lshl_add_u64 v[2:3], v[2:3], 0, v[10:11]
	s_mov_b32 s1, 0x9ab5000
	v_add_co_u32_e32 v10, vcc, s1, v2
	s_add_i32 s2, s2, s8
	s_nop 0
	v_addc_co_u32_e32 v11, vcc, 0, v3, vcc
	global_load_dwordx4 v[130:133], v[10:11], off
	s_or_b32 s1, s2, s18
	s_mov_b64 s[4:5], 0x9ab5000
	s_lshl_b32 s2, s1, 1
	s_mov_b32 s1, 0x9b39000
	v_lshl_add_u64 v[10:11], v[2:3], 0, s[4:5]
	v_add_co_u32_e32 v2, vcc, s1, v2
	global_load_dwordx4 v[134:137], v[10:11], off offset:32
	s_nop 0
	v_addc_co_u32_e32 v3, vcc, 0, v3, vcc
	global_load_dwordx4 v[138:141], v[2:3], off
	global_load_dwordx4 v[142:145], v[2:3], off offset:32
	s_ashr_i32 s3, s2, 31
	s_lshl_b64 s[2:3], s[2:3], 2
	v_lshl_add_u64 v[10:11], v[0:1], 0, s[2:3]
	v_ashrrev_i32_e32 v20, 8, v4
	v_readfirstlane_b32 s2, v10
	v_readfirstlane_b32 s3, v11
	s_lshl_b32 s0, s0, 6
	v_bfe_u32 v21, v4, 2, 6
	v_mul_i32_i24_e32 v10, 0x2100, v20
	s_mul_hi_i32 s17, s0, 0x4200
	s_mov_b64 s[0:1], 0xab35000
	global_load_dwordx2 v[12:13], v213, s[2:3]
	v_lshlrev_b32_e32 v2, 4, v4
	v_mul_hi_i32_i24_e32 v3, 0x2100, v20
	v_and_b32_e32 v16, 48, v2
	v_and_b32_e32 v18, 0x70, v2
	v_or_b32_e32 v2, v10, v21
	v_lshl_add_u64 v[10:11], v[0:1], 0, s[16:17]
	v_ashrrev_i32_e32 v7, 3, v4
	v_lshlrev_b64 v[2:3], 6, v[2:3]
	v_lshl_add_u64 v[10:11], v[10:11], 0, s[0:1]
	v_mov_b32_e32 v17, v129
	v_lshl_add_u64 v[8:9], v[8:9], 0, v[2:3]
	v_mad_i64_i32 v[10:11], s[0:1], v7, s13, v[10:11]
	v_lshl_add_u64 v[8:9], v[8:9], 0, v[16:17]
	s_mov_b32 s0, 0xa2f5000
	v_add_co_u32_e32 v8, vcc, s0, v8
	v_mov_b32_e32 v19, v129
	s_nop 0
	v_addc_co_u32_e32 v9, vcc, 0, v9, vcc
	v_lshl_add_u64 v[10:11], v[10:11], 0, v[18:19]
	global_load_dwordx4 v[146:149], v[8:9], off
	global_load_dwordx4 v[150:153], v[10:11], off
	s_mov_b32 s0, 0xf800000
	s_movk_i32 s21, 0x50
	s_waitcnt vmcnt(6)
	v_and_b32_e32 v9, 0xffff0000, v130
	v_lshlrev_b32_e32 v8, 16, v130
	v_mul_f32_e32 v9, v9, v9
	v_lshlrev_b32_e32 v10, 16, v131
	v_fmac_f32_e32 v9, v8, v8
	v_and_b32_e32 v11, 0xffff0000, v131
	v_fmac_f32_e32 v9, v10, v10
	v_lshlrev_b32_e32 v14, 16, v132
	v_fmac_f32_e32 v9, v11, v11
	v_and_b32_e32 v15, 0xffff0000, v132
	v_fmac_f32_e32 v9, v14, v14
	v_lshlrev_b32_e32 v17, 16, v133
	v_fmac_f32_e32 v9, v15, v15
	v_and_b32_e32 v19, 0xffff0000, v133
	v_fmac_f32_e32 v9, v17, v17
	s_waitcnt vmcnt(5)
	v_lshlrev_b32_e32 v22, 16, v134
	v_fmac_f32_e32 v9, v19, v19
	s_waitcnt vmcnt(4)
	v_and_b32_e32 v11, 0xffff0000, v138
	v_and_b32_e32 v23, 0xffff0000, v134
	v_fmac_f32_e32 v9, v22, v22
	v_lshlrev_b32_e32 v10, 16, v138
	v_mul_f32_e32 v14, v11, v11
	v_lshlrev_b32_e32 v24, 16, v135
	v_fmac_f32_e32 v9, v23, v23
	v_fmac_f32_e32 v14, v10, v10
	v_lshlrev_b32_e32 v10, 16, v139
	v_and_b32_e32 v25, 0xffff0000, v135
	v_fmac_f32_e32 v9, v24, v24
	v_fmac_f32_e32 v14, v10, v10
	v_and_b32_e32 v10, 0xffff0000, v139
	v_lshlrev_b32_e32 v26, 16, v136
	v_fmac_f32_e32 v9, v25, v25
	v_fmac_f32_e32 v14, v10, v10
	v_lshlrev_b32_e32 v10, 16, v140
	v_and_b32_e32 v27, 0xffff0000, v136
	v_fmac_f32_e32 v9, v26, v26
	v_fmac_f32_e32 v14, v10, v10
	v_and_b32_e32 v10, 0xffff0000, v140
	v_lshlrev_b32_e32 v28, 16, v137
	v_fmac_f32_e32 v9, v27, v27
	v_fmac_f32_e32 v14, v10, v10
	v_lshlrev_b32_e32 v10, 16, v141
	v_and_b32_e32 v29, 0xffff0000, v137
	v_fmac_f32_e32 v9, v28, v28
	v_fmac_f32_e32 v14, v10, v10
	v_and_b32_e32 v10, 0xffff0000, v141
	v_fmac_f32_e32 v9, v29, v29
	v_fmac_f32_e32 v14, v10, v10
	s_waitcnt vmcnt(3)
	v_lshlrev_b32_e32 v10, 16, v142
	ds_bpermute_b32 v8, v194, v9
	v_fmac_f32_e32 v14, v10, v10
	v_and_b32_e32 v10, 0xffff0000, v142
	v_fmac_f32_e32 v14, v10, v10
	v_lshlrev_b32_e32 v10, 16, v143
	v_fmac_f32_e32 v14, v10, v10
	v_and_b32_e32 v10, 0xffff0000, v143
	v_fmac_f32_e32 v14, v10, v10
	v_lshlrev_b32_e32 v10, 16, v144
	v_fmac_f32_e32 v14, v10, v10
	v_and_b32_e32 v10, 0xffff0000, v144
	s_waitcnt lgkmcnt(0)
	v_add_f32_e32 v8, v9, v8
	v_fmac_f32_e32 v14, v10, v10
	v_lshlrev_b32_e32 v10, 16, v145
	s_waitcnt vmcnt(2)
	v_mul_f32_e32 v8, v12, v8
	v_fmac_f32_e32 v14, v10, v10
	v_and_b32_e32 v10, 0xffff0000, v145
	v_mul_f32_e32 v9, 0x4f800000, v8
	v_cmp_gt_f32_e32 vcc, s0, v8
	v_fmac_f32_e32 v14, v10, v10
	ds_bpermute_b32 v10, v194, v14
	v_cndmask_b32_e32 v8, v8, v9, vcc
	v_sqrt_f32_e32 v9, v8
	s_waitcnt lgkmcnt(0)
	v_add_f32_e32 v10, v14, v10
	v_add_u32_e32 v11, -1, v9
	v_fma_f32 v12, -v11, v9, v8
	v_mul_f32_e32 v10, v13, v10
	v_cmp_ge_f32_e64 s[2:3], 0, v12
	v_mul_f32_e32 v12, 0x4f800000, v10
	v_cmp_gt_f32_e64 s[0:1], s0, v10
	v_add_u32_e32 v14, 1, v9
	v_fma_f32 v13, -v14, v9, v8
	v_cndmask_b32_e64 v10, v10, v12, s[0:1]
	v_sqrt_f32_e32 v12, v10
	v_cmp_lt_f32_e64 s[6:7], 0, v13
	v_add_u32_e32 v13, -1, v12
	v_fma_f32 v15, -v13, v12, v10
	v_cmp_ge_f32_e64 s[4:5], 0, v15
	v_add_u32_e32 v15, 1, v12
	v_fma_f32 v17, -v15, v12, v10
	v_cmp_lt_f32_e64 s[10:11], 0, v17
	v_lshl_or_b32 v17, v20, 6, v21
	v_mul_lo_u32 v17, v17, s21
	v_add3_u32 v155, s57, v17, v16
	v_mul_lo_u32 v16, v7, s59
	v_readfirstlane_b32 s21, v4
	v_add3_u32 v157, s57, v16, v18
	s_cmpk_lt_i32 s21, 0x100
	s_waitcnt vmcnt(1)
	ds_write_b128 v155, v[146:149]
	s_waitcnt vmcnt(0)
	ds_write_b128 v157, v[150:153] offset:10240
	s_waitcnt lgkmcnt(0)
	s_barrier
	s_cbranch_scc1 .LBB0_607
	s_setprio 0

.Lat_loop:
	global_load_dwordx4 v[146:149], v[160:161], off
	global_load_dwordx4 v[150:153], v[162:163], off
	v_lshl_add_u64 v[160:161], v[160:161], 0, s[54:55]
	v_lshl_add_u64 v[162:163], v[162:163], 0, s[88:89]
	s_waitcnt lgkmcnt(2)
	v_mfma_f32_32x32x16_bf16 v[112:127], v[164:167], v[138:141], v[80:95]
	v_exp_f32_e32 v96, v96
	v_exp_f32_e32 v97, v97
	v_mfma_f32_32x32x16_bf16 v[112:127], v[168:171], v[142:145], v[112:127]
	ds_read_b128 v[164:167], v175 offset:2560
	ds_read_b128 v[168:171], v175 offset:2592
	v_exp_f32_e32 v98, v98
	v_exp_f32_e32 v99, v99
	v_exp_f32_e32 v100, v100
	v_mfma_f32_32x32x16_bf16 v[32:47], v[226:229], v[184:187], v[32:47]
	ds_read_b128 v[226:229], v174 offset:10240
	v_exp_f32_e32 v101, v101
	v_exp_f32_e32 v102, v102
	v_exp_f32_e32 v103, v103
	v_mfma_f32_32x32x16_bf16 v[0:15], v[234:237], v[184:187], v[0:15]
	ds_read_b128 v[234:237], v174 offset:14848
	v_exp_f32_e32 v104, v104
	v_exp_f32_e32 v105, v105
	v_exp_f32_e32 v106, v106
	v_mfma_f32_32x32x16_bf16 v[32:47], v[230:233], v[188:191], v[32:47]
	ds_read_b128 v[230:233], v174 offset:10272
	v_exp_f32_e32 v107, v107
	v_exp_f32_e32 v108, v108
	v_exp_f32_e32 v109, v109
	v_mfma_f32_32x32x16_bf16 v[0:15], v[238:241], v[188:191], v[0:15]
	ds_read_b128 v[238:241], v174 offset:14880
	v_exp_f32_e32 v110, v110
	v_exp_f32_e32 v111, v111
	v_pk_add_f32 v[200:201], v[96:97], v[200:201]
	v_cvt_pk_bf16_f32 v176, v96, v97
	v_pk_add_f32 v[200:201], v[98:99], v[200:201]
	v_cvt_pk_bf16_f32 v177, v98, v99
	v_pk_add_f32 v[200:201], v[100:101], v[200:201]
	v_cvt_pk_bf16_f32 v178, v100, v101
	v_pk_add_f32 v[200:201], v[102:103], v[200:201]
	v_cvt_pk_bf16_f32 v179, v102, v103
	v_pk_add_f32 v[200:201], v[104:105], v[200:201]
	v_cvt_pk_bf16_f32 v180, v104, v105
	v_pk_add_f32 v[200:201], v[106:107], v[200:201]
	v_cvt_pk_bf16_f32 v181, v106, v107
	v_pk_add_f32 v[200:201], v[108:109], v[200:201]
	v_cvt_pk_bf16_f32 v182, v108, v109
	v_pk_add_f32 v[200:201], v[110:111], v[200:201]
	v_cvt_pk_bf16_f32 v183, v110, v111
	s_waitcnt lgkmcnt(4)
	v_mfma_f32_32x32x16_bf16 v[96:111], v[164:167], v[130:133], v[64:79]
	v_exp_f32_e32 v112, v112
	v_exp_f32_e32 v113, v113
	v_mfma_f32_32x32x16_bf16 v[96:111], v[168:171], v[134:137], v[96:111]
	ds_read_b128 v[164:167], v175 offset:7680
	ds_read_b128 v[168:171], v175 offset:7712
	v_exp_f32_e32 v114, v114
	v_exp_f32_e32 v115, v115
	v_exp_f32_e32 v116, v116
	s_waitcnt lgkmcnt(2)
	v_mfma_f32_32x32x16_bf16 v[48:63], v[226:229], v[176:179], v[48:63]
	v_exp_f32_e32 v117, v117
	v_exp_f32_e32 v118, v118
	v_exp_f32_e32 v119, v119
	v_mfma_f32_32x32x16_bf16 v[16:31], v[234:237], v[176:179], v[16:31]
	v_exp_f32_e32 v120, v120
	v_exp_f32_e32 v121, v121
	v_exp_f32_e32 v122, v122
	v_mfma_f32_32x32x16_bf16 v[48:63], v[230:233], v[180:183], v[48:63]
	v_exp_f32_e32 v123, v123
	v_exp_f32_e32 v124, v124
	v_exp_f32_e32 v125, v125
	v_mfma_f32_32x32x16_bf16 v[16:31], v[238:241], v[180:183], v[16:31]
	v_exp_f32_e32 v126, v126
	v_exp_f32_e32 v127, v127
	v_pk_add_f32 v[202:203], v[112:113], v[202:203]
	v_cvt_pk_bf16_f32 v184, v112, v113
	v_pk_add_f32 v[202:203], v[114:115], v[202:203]
	v_cvt_pk_bf16_f32 v185, v114, v115
	v_pk_add_f32 v[202:203], v[116:117], v[202:203]
	v_cvt_pk_bf16_f32 v186, v116, v117
	v_pk_add_f32 v[202:203], v[118:119], v[202:203]
	v_cvt_pk_bf16_f32 v187, v118, v119
	v_pk_add_f32 v[202:203], v[120:121], v[202:203]
	v_cvt_pk_bf16_f32 v188, v120, v121
	v_pk_add_f32 v[202:203], v[122:123], v[202:203]
	v_cvt_pk_bf16_f32 v189, v122, v123
	v_pk_add_f32 v[202:203], v[124:125], v[202:203]
	v_cvt_pk_bf16_f32 v190, v124, v125
	v_pk_add_f32 v[202:203], v[126:127], v[202:203]
	v_cvt_pk_bf16_f32 v191, v126, v127
	s_waitcnt lgkmcnt(0)
	v_mfma_f32_32x32x16_bf16 v[112:127], v[164:167], v[138:141], v[80:95]
	v_exp_f32_e32 v96, v96
	v_exp_f32_e32 v97, v97
	v_mfma_f32_32x32x16_bf16 v[112:127], v[168:171], v[142:145], v[112:127]
	s_barrier
	ds_read_b128 v[164:167], v175 offset:19456
	ds_read_b128 v[168:171], v175 offset:19488
	v_exp_f32_e32 v98, v98
	v_exp_f32_e32 v99, v99
	v_exp_f32_e32 v100, v100
	v_mfma_f32_32x32x16_bf16 v[32:47], v[226:229], v[184:187], v[32:47]
	ds_read_b128 v[226:229], v174 offset:10304
	v_exp_f32_e32 v101, v101
	v_exp_f32_e32 v102, v102
	v_exp_f32_e32 v103, v103
	v_mfma_f32_32x32x16_bf16 v[0:15], v[234:237], v[184:187], v[0:15]
	ds_read_b128 v[234:237], v174 offset:14912
	v_exp_f32_e32 v104, v104
	v_exp_f32_e32 v105, v105
	v_exp_f32_e32 v106, v106
	v_mfma_f32_32x32x16_bf16 v[32:47], v[230:233], v[188:191], v[32:47]
	ds_read_b128 v[230:233], v174 offset:10336
	v_exp_f32_e32 v107, v107
	v_exp_f32_e32 v108, v108
	v_exp_f32_e32 v109, v109
	v_mfma_f32_32x32x16_bf16 v[0:15], v[238:241], v[188:191], v[0:15]
	ds_read_b128 v[238:241], v174 offset:14944
	v_exp_f32_e32 v110, v110
	v_exp_f32_e32 v111, v111
	v_pk_add_f32 v[200:201], v[96:97], v[200:201]
	v_cvt_pk_bf16_f32 v176, v96, v97
	v_pk_add_f32 v[200:201], v[98:99], v[200:201]
	v_cvt_pk_bf16_f32 v177, v98, v99
	v_pk_add_f32 v[200:201], v[100:101], v[200:201]
	v_cvt_pk_bf16_f32 v178, v100, v101
	v_pk_add_f32 v[200:201], v[102:103], v[200:201]
	v_cvt_pk_bf16_f32 v179, v102, v103
	v_pk_add_f32 v[200:201], v[104:105], v[200:201]
	v_cvt_pk_bf16_f32 v180, v104, v105
	v_pk_add_f32 v[200:201], v[106:107], v[200:201]
	v_cvt_pk_bf16_f32 v181, v106, v107
	v_pk_add_f32 v[200:201], v[108:109], v[200:201]
	v_cvt_pk_bf16_f32 v182, v108, v109
	v_pk_add_f32 v[200:201], v[110:111], v[200:201]
	v_cvt_pk_bf16_f32 v183, v110, v111
	s_waitcnt lgkmcnt(4)
	v_mfma_f32_32x32x16_bf16 v[96:111], v[164:167], v[130:133], v[64:79]
	v_exp_f32_e32 v112, v112
	v_exp_f32_e32 v113, v113
	v_mfma_f32_32x32x16_bf16 v[96:111], v[168:171], v[134:137], v[96:111]
	ds_read_b128 v[164:167], v175 offset:24576
	ds_read_b128 v[168:171], v175 offset:24608
	v_exp_f32_e32 v114, v114
	v_exp_f32_e32 v115, v115
	v_exp_f32_e32 v116, v116
	s_waitcnt lgkmcnt(2)
	v_mfma_f32_32x32x16_bf16 v[48:63], v[226:229], v[176:179], v[48:63]
	v_exp_f32_e32 v117, v117
	v_exp_f32_e32 v118, v118
	v_exp_f32_e32 v119, v119
	v_mfma_f32_32x32x16_bf16 v[16:31], v[234:237], v[176:179], v[16:31]
	v_exp_f32_e32 v120, v120
	v_exp_f32_e32 v121, v121
	v_exp_f32_e32 v122, v122
	v_mfma_f32_32x32x16_bf16 v[48:63], v[230:233], v[180:183], v[48:63]
	v_exp_f32_e32 v123, v123
	v_exp_f32_e32 v124, v124
	v_exp_f32_e32 v125, v125
	v_mfma_f32_32x32x16_bf16 v[16:31], v[238:241], v[180:183], v[16:31]
	s_waitcnt vmcnt(1)
	ds_write_b128 v155, v[146:149] offset:38912
	s_waitcnt vmcnt(0)
	ds_write_b128 v157, v[150:153] offset:49152
	v_exp_f32_e32 v126, v126
	v_exp_f32_e32 v127, v127
	v_pk_add_f32 v[202:203], v[112:113], v[202:203]
	v_cvt_pk_bf16_f32 v184, v112, v113
	v_pk_add_f32 v[202:203], v[114:115], v[202:203]
	v_cvt_pk_bf16_f32 v185, v114, v115
	v_pk_add_f32 v[202:203], v[116:117], v[202:203]
	v_cvt_pk_bf16_f32 v186, v116, v117
	v_pk_add_f32 v[202:203], v[118:119], v[202:203]
	v_cvt_pk_bf16_f32 v187, v118, v119
	v_pk_add_f32 v[202:203], v[120:121], v[202:203]
	v_cvt_pk_bf16_f32 v188, v120, v121
	v_pk_add_f32 v[202:203], v[122:123], v[202:203]
	v_cvt_pk_bf16_f32 v189, v122, v123
	v_pk_add_f32 v[202:203], v[124:125], v[202:203]
	v_cvt_pk_bf16_f32 v190, v124, v125
	v_pk_add_f32 v[202:203], v[126:127], v[202:203]
	v_cvt_pk_bf16_f32 v191, v126, v127
	s_cmp_eq_u32 s2, 43
	s_cbranch_scc1 .Lat_skip1
	global_load_dwordx4 v[146:149], v[160:161], off
	global_load_dwordx4 v[150:153], v[162:163], off
	v_lshl_add_u64 v[160:161], v[160:161], 0, s[54:55]
	v_lshl_add_u64 v[162:163], v[162:163], 0, s[88:89]
.Lat_skip1:
	s_waitcnt lgkmcnt(2)
	v_mfma_f32_32x32x16_bf16 v[112:127], v[164:167], v[138:141], v[80:95]
	v_exp_f32_e32 v96, v96
	v_exp_f32_e32 v97, v97
	v_mfma_f32_32x32x16_bf16 v[112:127], v[168:171], v[142:145], v[112:127]
	ds_read_b128 v[164:167], v175 offset:22016
	ds_read_b128 v[168:171], v175 offset:22048
	v_exp_f32_e32 v98, v98
	v_exp_f32_e32 v99, v99
	v_exp_f32_e32 v100, v100
	v_mfma_f32_32x32x16_bf16 v[32:47], v[226:229], v[184:187], v[32:47]
	ds_read_b128 v[226:229], v174 offset:29696
	v_exp_f32_e32 v101, v101
	v_exp_f32_e32 v102, v102
	v_exp_f32_e32 v103, v103
	v_mfma_f32_32x32x16_bf16 v[0:15], v[234:237], v[184:187], v[0:15]
	ds_read_b128 v[234:237], v174 offset:34304
	v_exp_f32_e32 v104, v104
	v_exp_f32_e32 v105, v105
	v_exp_f32_e32 v106, v106
	v_mfma_f32_32x32x16_bf16 v[32:47], v[230:233], v[188:191], v[32:47]
	ds_read_b128 v[230:233], v174 offset:29728
	v_exp_f32_e32 v107, v107
	v_exp_f32_e32 v108, v108
	v_exp_f32_e32 v109, v109
	v_mfma_f32_32x32x16_bf16 v[0:15], v[238:241], v[188:191], v[0:15]
	ds_read_b128 v[238:241], v174 offset:34336
	v_exp_f32_e32 v110, v110
	v_exp_f32_e32 v111, v111
	v_pk_add_f32 v[200:201], v[96:97], v[200:201]
	v_cvt_pk_bf16_f32 v176, v96, v97
	v_pk_add_f32 v[200:201], v[98:99], v[200:201]
	v_cvt_pk_bf16_f32 v177, v98, v99
	v_pk_add_f32 v[200:201], v[100:101], v[200:201]
	v_cvt_pk_bf16_f32 v178, v100, v101
	v_pk_add_f32 v[200:201], v[102:103], v[200:201]
	v_cvt_pk_bf16_f32 v179, v102, v103
	v_pk_add_f32 v[200:201], v[104:105], v[200:201]
	v_cvt_pk_bf16_f32 v180, v104, v105
	v_pk_add_f32 v[200:201], v[106:107], v[200:201]
	v_cvt_pk_bf16_f32 v181, v106, v107
	v_pk_add_f32 v[200:201], v[108:109], v[200:201]
	v_cvt_pk_bf16_f32 v182, v108, v109
	v_pk_add_f32 v[200:201], v[110:111], v[200:201]
	v_cvt_pk_bf16_f32 v183, v110, v111
	s_waitcnt lgkmcnt(4)
	v_mfma_f32_32x32x16_bf16 v[96:111], v[164:167], v[130:133], v[64:79]
	v_exp_f32_e32 v112, v112
	v_exp_f32_e32 v113, v113
	v_mfma_f32_32x32x16_bf16 v[96:111], v[168:171], v[134:137], v[96:111]
	ds_read_b128 v[164:167], v175 offset:27136
	ds_read_b128 v[168:171], v175 offset:27168
	v_exp_f32_e32 v114, v114
	v_exp_f32_e32 v115, v115
	v_exp_f32_e32 v116, v116
	s_waitcnt lgkmcnt(2)
	v_mfma_f32_32x32x16_bf16 v[48:63], v[226:229], v[176:179], v[48:63]
	v_exp_f32_e32 v117, v117
	v_exp_f32_e32 v118, v118
	v_exp_f32_e32 v119, v119
	v_mfma_f32_32x32x16_bf16 v[16:31], v[234:237], v[176:179], v[16:31]
	v_exp_f32_e32 v120, v120
	v_exp_f32_e32 v121, v121
	v_exp_f32_e32 v122, v122
	v_mfma_f32_32x32x16_bf16 v[48:63], v[230:233], v[180:183], v[48:63]
	v_exp_f32_e32 v123, v123
	v_exp_f32_e32 v124, v124
	v_exp_f32_e32 v125, v125
	v_mfma_f32_32x32x16_bf16 v[16:31], v[238:241], v[180:183], v[16:31]
	v_exp_f32_e32 v126, v126
	v_exp_f32_e32 v127, v127
	v_pk_add_f32 v[202:203], v[112:113], v[202:203]
	v_cvt_pk_bf16_f32 v184, v112, v113
	v_pk_add_f32 v[202:203], v[114:115], v[202:203]
	v_cvt_pk_bf16_f32 v185, v114, v115
	v_pk_add_f32 v[202:203], v[116:117], v[202:203]
	v_cvt_pk_bf16_f32 v186, v116, v117
	v_pk_add_f32 v[202:203], v[118:119], v[202:203]
	v_cvt_pk_bf16_f32 v187, v118, v119
	v_pk_add_f32 v[202:203], v[120:121], v[202:203]
	v_cvt_pk_bf16_f32 v188, v120, v121
	v_pk_add_f32 v[202:203], v[122:123], v[202:203]
	v_cvt_pk_bf16_f32 v189, v122, v123
	v_pk_add_f32 v[202:203], v[124:125], v[202:203]
	v_cvt_pk_bf16_f32 v190, v124, v125
	v_pk_add_f32 v[202:203], v[126:127], v[202:203]
	v_cvt_pk_bf16_f32 v191, v126, v127
	s_waitcnt lgkmcnt(0)
	v_mfma_f32_32x32x16_bf16 v[112:127], v[164:167], v[138:141], v[80:95]
	v_exp_f32_e32 v96, v96
	v_exp_f32_e32 v97, v97
	v_mfma_f32_32x32x16_bf16 v[112:127], v[168:171], v[142:145], v[112:127]
	s_barrier
	ds_read_b128 v[164:167], v175 offset:38912
	ds_read_b128 v[168:171], v175 offset:38944
	v_exp_f32_e32 v98, v98
	v_exp_f32_e32 v99, v99
	v_exp_f32_e32 v100, v100
	v_mfma_f32_32x32x16_bf16 v[32:47], v[226:229], v[184:187], v[32:47]
	ds_read_b128 v[226:229], v174 offset:29760
	v_exp_f32_e32 v101, v101
	v_exp_f32_e32 v102, v102
	v_exp_f32_e32 v103, v103
	v_mfma_f32_32x32x16_bf16 v[0:15], v[234:237], v[184:187], v[0:15]
	ds_read_b128 v[234:237], v174 offset:34368
	v_exp_f32_e32 v104, v104
	v_exp_f32_e32 v105, v105
	v_exp_f32_e32 v106, v106
	v_mfma_f32_32x32x16_bf16 v[32:47], v[230:233], v[188:191], v[32:47]
	ds_read_b128 v[230:233], v174 offset:29792
	v_exp_f32_e32 v107, v107
	v_exp_f32_e32 v108, v108
	v_exp_f32_e32 v109, v109
	v_mfma_f32_32x32x16_bf16 v[0:15], v[238:241], v[188:191], v[0:15]
	ds_read_b128 v[238:241], v174 offset:34400
	v_exp_f32_e32 v110, v110
	v_exp_f32_e32 v111, v111
	v_pk_add_f32 v[200:201], v[96:97], v[200:201]
	v_cvt_pk_bf16_f32 v176, v96, v97
	v_pk_add_f32 v[200:201], v[98:99], v[200:201]
	v_cvt_pk_bf16_f32 v177, v98, v99
	v_pk_add_f32 v[200:201], v[100:101], v[200:201]
	v_cvt_pk_bf16_f32 v178, v100, v101
	v_pk_add_f32 v[200:201], v[102:103], v[200:201]
	v_cvt_pk_bf16_f32 v179, v102, v103
	v_pk_add_f32 v[200:201], v[104:105], v[200:201]
	v_cvt_pk_bf16_f32 v180, v104, v105
	v_pk_add_f32 v[200:201], v[106:107], v[200:201]
	v_cvt_pk_bf16_f32 v181, v106, v107
	v_pk_add_f32 v[200:201], v[108:109], v[200:201]
	v_cvt_pk_bf16_f32 v182, v108, v109
	v_pk_add_f32 v[200:201], v[110:111], v[200:201]
	v_cvt_pk_bf16_f32 v183, v110, v111
	s_waitcnt lgkmcnt(4)
	v_mfma_f32_32x32x16_bf16 v[96:111], v[164:167], v[130:133], v[64:79]
	v_exp_f32_e32 v112, v112
	v_exp_f32_e32 v113, v113
	v_mfma_f32_32x32x16_bf16 v[96:111], v[168:171], v[134:137], v[96:111]
	ds_read_b128 v[164:167], v175 offset:44032
	ds_read_b128 v[168:171], v175 offset:44064
	v_exp_f32_e32 v114, v114
	v_exp_f32_e32 v115, v115
	v_exp_f32_e32 v116, v116
	s_waitcnt lgkmcnt(2)
	v_mfma_f32_32x32x16_bf16 v[48:63], v[226:229], v[176:179], v[48:63]
	v_exp_f32_e32 v117, v117
	v_exp_f32_e32 v118, v118
	v_exp_f32_e32 v119, v119
	v_mfma_f32_32x32x16_bf16 v[16:31], v[234:237], v[176:179], v[16:31]
	v_exp_f32_e32 v120, v120
	v_exp_f32_e32 v121, v121
	v_exp_f32_e32 v122, v122
	v_mfma_f32_32x32x16_bf16 v[48:63], v[230:233], v[180:183], v[48:63]
	v_exp_f32_e32 v123, v123
	v_exp_f32_e32 v124, v124
	v_exp_f32_e32 v125, v125
	v_mfma_f32_32x32x16_bf16 v[16:31], v[238:241], v[180:183], v[16:31]
	s_waitcnt vmcnt(1)
	ds_write_b128 v155, v[146:149] offset:0
	s_waitcnt vmcnt(0)
	ds_write_b128 v157, v[150:153] offset:10240
	v_exp_f32_e32 v126, v126
	v_exp_f32_e32 v127, v127
	v_pk_add_f32 v[202:203], v[112:113], v[202:203]
	v_cvt_pk_bf16_f32 v184, v112, v113
	v_pk_add_f32 v[202:203], v[114:115], v[202:203]
	v_cvt_pk_bf16_f32 v185, v114, v115
	v_pk_add_f32 v[202:203], v[116:117], v[202:203]
	v_cvt_pk_bf16_f32 v186, v116, v117
	v_pk_add_f32 v[202:203], v[118:119], v[202:203]
	v_cvt_pk_bf16_f32 v187, v118, v119
	v_pk_add_f32 v[202:203], v[120:121], v[202:203]
	v_cvt_pk_bf16_f32 v188, v120, v121
	v_pk_add_f32 v[202:203], v[122:123], v[202:203]
	v_cvt_pk_bf16_f32 v189, v122, v123
	v_pk_add_f32 v[202:203], v[124:125], v[202:203]
	v_cvt_pk_bf16_f32 v190, v124, v125
	v_pk_add_f32 v[202:203], v[126:127], v[202:203]
	v_cvt_pk_bf16_f32 v191, v126, v127
	s_cmp_eq_u32 s2, 43
	s_cbranch_scc1 .Lat_skip2
	global_load_dwordx4 v[146:149], v[160:161], off
	global_load_dwordx4 v[150:153], v[162:163], off
	v_lshl_add_u64 v[160:161], v[160:161], 0, s[54:55]
	v_lshl_add_u64 v[162:163], v[162:163], 0, s[88:89]
.Lat_skip2:
	s_waitcnt lgkmcnt(2)
	v_mfma_f32_32x32x16_bf16 v[112:127], v[164:167], v[138:141], v[80:95]
	v_exp_f32_e32 v96, v96
	v_exp_f32_e32 v97, v97
	v_mfma_f32_32x32x16_bf16 v[112:127], v[168:171], v[142:145], v[112:127]
	ds_read_b128 v[164:167], v175 offset:41472
	ds_read_b128 v[168:171], v175 offset:41504
	v_exp_f32_e32 v98, v98
	v_exp_f32_e32 v99, v99
	v_exp_f32_e32 v100, v100
	v_mfma_f32_32x32x16_bf16 v[32:47], v[226:229], v[184:187], v[32:47]
	ds_read_b128 v[226:229], v174 offset:49152
	v_exp_f32_e32 v101, v101
	v_exp_f32_e32 v102, v102
	v_exp_f32_e32 v103, v103
	v_mfma_f32_32x32x16_bf16 v[0:15], v[234:237], v[184:187], v[0:15]
	ds_read_b128 v[234:237], v174 offset:53760
	v_exp_f32_e32 v104, v104
	v_exp_f32_e32 v105, v105
	v_exp_f32_e32 v106, v106
	v_mfma_f32_32x32x16_bf16 v[32:47], v[230:233], v[188:191], v[32:47]
	ds_read_b128 v[230:233], v174 offset:49184
	v_exp_f32_e32 v107, v107
	v_exp_f32_e32 v108, v108
	v_exp_f32_e32 v109, v109
	v_mfma_f32_32x32x16_bf16 v[0:15], v[238:241], v[188:191], v[0:15]
	ds_read_b128 v[238:241], v174 offset:53792
	v_exp_f32_e32 v110, v110
	v_exp_f32_e32 v111, v111
	v_pk_add_f32 v[200:201], v[96:97], v[200:201]
	v_cvt_pk_bf16_f32 v176, v96, v97
	v_pk_add_f32 v[200:201], v[98:99], v[200:201]
	v_cvt_pk_bf16_f32 v177, v98, v99
	v_pk_add_f32 v[200:201], v[100:101], v[200:201]
	v_cvt_pk_bf16_f32 v178, v100, v101
	v_pk_add_f32 v[200:201], v[102:103], v[200:201]
	v_cvt_pk_bf16_f32 v179, v102, v103
	v_pk_add_f32 v[200:201], v[104:105], v[200:201]
	v_cvt_pk_bf16_f32 v180, v104, v105
	v_pk_add_f32 v[200:201], v[106:107], v[200:201]
	v_cvt_pk_bf16_f32 v181, v106, v107
	v_pk_add_f32 v[200:201], v[108:109], v[200:201]
	v_cvt_pk_bf16_f32 v182, v108, v109
	v_pk_add_f32 v[200:201], v[110:111], v[200:201]
	v_cvt_pk_bf16_f32 v183, v110, v111
	s_waitcnt lgkmcnt(4)
	v_mfma_f32_32x32x16_bf16 v[96:111], v[164:167], v[130:133], v[64:79]
	v_exp_f32_e32 v112, v112
	v_exp_f32_e32 v113, v113
	v_mfma_f32_32x32x16_bf16 v[96:111], v[168:171], v[134:137], v[96:111]
	ds_read_b128 v[164:167], v175 offset:46592
	ds_read_b128 v[168:171], v175 offset:46624
	v_exp_f32_e32 v114, v114
	v_exp_f32_e32 v115, v115
	v_exp_f32_e32 v116, v116
	s_waitcnt lgkmcnt(2)
	v_mfma_f32_32x32x16_bf16 v[48:63], v[226:229], v[176:179], v[48:63]
	v_exp_f32_e32 v117, v117
	v_exp_f32_e32 v118, v118
	v_exp_f32_e32 v119, v119
	v_mfma_f32_32x32x16_bf16 v[16:31], v[234:237], v[176:179], v[16:31]
	v_exp_f32_e32 v120, v120
	v_exp_f32_e32 v121, v121
	v_exp_f32_e32 v122, v122
	v_mfma_f32_32x32x16_bf16 v[48:63], v[230:233], v[180:183], v[48:63]
	v_exp_f32_e32 v123, v123
	v_exp_f32_e32 v124, v124
	v_exp_f32_e32 v125, v125
	v_mfma_f32_32x32x16_bf16 v[16:31], v[238:241], v[180:183], v[16:31]
	v_exp_f32_e32 v126, v126
	v_exp_f32_e32 v127, v127
	v_pk_add_f32 v[202:203], v[112:113], v[202:203]
	v_cvt_pk_bf16_f32 v184, v112, v113
	v_pk_add_f32 v[202:203], v[114:115], v[202:203]
	v_cvt_pk_bf16_f32 v185, v114, v115
	v_pk_add_f32 v[202:203], v[116:117], v[202:203]
	v_cvt_pk_bf16_f32 v186, v116, v117
	v_pk_add_f32 v[202:203], v[118:119], v[202:203]
	v_cvt_pk_bf16_f32 v187, v118, v119
	v_pk_add_f32 v[202:203], v[120:121], v[202:203]
	v_cvt_pk_bf16_f32 v188, v120, v121
	v_pk_add_f32 v[202:203], v[122:123], v[202:203]
	v_cvt_pk_bf16_f32 v189, v122, v123
	v_pk_add_f32 v[202:203], v[124:125], v[202:203]
	v_cvt_pk_bf16_f32 v190, v124, v125
	v_pk_add_f32 v[202:203], v[126:127], v[202:203]
	v_cvt_pk_bf16_f32 v191, v126, v127
	s_waitcnt lgkmcnt(0)
	v_mfma_f32_32x32x16_bf16 v[112:127], v[164:167], v[138:141], v[80:95]
	v_exp_f32_e32 v96, v96
	v_exp_f32_e32 v97, v97
	v_mfma_f32_32x32x16_bf16 v[112:127], v[168:171], v[142:145], v[112:127]
	s_barrier
	ds_read_b128 v[164:167], v175 offset:0
	ds_read_b128 v[168:171], v175 offset:32
	v_exp_f32_e32 v98, v98
	v_exp_f32_e32 v99, v99
	v_exp_f32_e32 v100, v100
	v_mfma_f32_32x32x16_bf16 v[32:47], v[226:229], v[184:187], v[32:47]
	ds_read_b128 v[226:229], v174 offset:49216
	v_exp_f32_e32 v101, v101
	v_exp_f32_e32 v102, v102
	v_exp_f32_e32 v103, v103
	v_mfma_f32_32x32x16_bf16 v[0:15], v[234:237], v[184:187], v[0:15]
	ds_read_b128 v[234:237], v174 offset:53824
	v_exp_f32_e32 v104, v104
	v_exp_f32_e32 v105, v105
	v_exp_f32_e32 v106, v106
	v_mfma_f32_32x32x16_bf16 v[32:47], v[230:233], v[188:191], v[32:47]
	ds_read_b128 v[230:233], v174 offset:49248
	v_exp_f32_e32 v107, v107
	v_exp_f32_e32 v108, v108
	v_exp_f32_e32 v109, v109
	v_mfma_f32_32x32x16_bf16 v[0:15], v[238:241], v[188:191], v[0:15]
	ds_read_b128 v[238:241], v174 offset:53856
	v_exp_f32_e32 v110, v110
	v_exp_f32_e32 v111, v111
	v_pk_add_f32 v[200:201], v[96:97], v[200:201]
	v_cvt_pk_bf16_f32 v176, v96, v97
	v_pk_add_f32 v[200:201], v[98:99], v[200:201]
	v_cvt_pk_bf16_f32 v177, v98, v99
	v_pk_add_f32 v[200:201], v[100:101], v[200:201]
	v_cvt_pk_bf16_f32 v178, v100, v101
	v_pk_add_f32 v[200:201], v[102:103], v[200:201]
	v_cvt_pk_bf16_f32 v179, v102, v103
	v_pk_add_f32 v[200:201], v[104:105], v[200:201]
	v_cvt_pk_bf16_f32 v180, v104, v105
	v_pk_add_f32 v[200:201], v[106:107], v[200:201]
	v_cvt_pk_bf16_f32 v181, v106, v107
	v_pk_add_f32 v[200:201], v[108:109], v[200:201]
	v_cvt_pk_bf16_f32 v182, v108, v109
	v_pk_add_f32 v[200:201], v[110:111], v[200:201]
	v_cvt_pk_bf16_f32 v183, v110, v111
	s_waitcnt lgkmcnt(4)
	v_mfma_f32_32x32x16_bf16 v[96:111], v[164:167], v[130:133], v[64:79]
	v_exp_f32_e32 v112, v112
	v_exp_f32_e32 v113, v113
	v_mfma_f32_32x32x16_bf16 v[96:111], v[168:171], v[134:137], v[96:111]
	ds_read_b128 v[164:167], v175 offset:5120
	ds_read_b128 v[168:171], v175 offset:5152
	v_exp_f32_e32 v114, v114
	v_exp_f32_e32 v115, v115
	v_exp_f32_e32 v116, v116
	s_waitcnt lgkmcnt(2)
	v_mfma_f32_32x32x16_bf16 v[48:63], v[226:229], v[176:179], v[48:63]
	v_exp_f32_e32 v117, v117
	v_exp_f32_e32 v118, v118
	v_exp_f32_e32 v119, v119
	v_mfma_f32_32x32x16_bf16 v[16:31], v[234:237], v[176:179], v[16:31]
	v_exp_f32_e32 v120, v120
	v_exp_f32_e32 v121, v121
	v_exp_f32_e32 v122, v122
	v_mfma_f32_32x32x16_bf16 v[48:63], v[230:233], v[180:183], v[48:63]
	v_exp_f32_e32 v123, v123
	v_exp_f32_e32 v124, v124
	v_exp_f32_e32 v125, v125
	v_mfma_f32_32x32x16_bf16 v[16:31], v[238:241], v[180:183], v[16:31]
	s_waitcnt vmcnt(1)
	ds_write_b128 v155, v[146:149] offset:19456
	s_waitcnt vmcnt(0)
	ds_write_b128 v157, v[150:153] offset:29696
	v_exp_f32_e32 v126, v126
	v_exp_f32_e32 v127, v127
	v_pk_add_f32 v[202:203], v[112:113], v[202:203]
	v_cvt_pk_bf16_f32 v184, v112, v113
	v_pk_add_f32 v[202:203], v[114:115], v[202:203]
	v_cvt_pk_bf16_f32 v185, v114, v115
	v_pk_add_f32 v[202:203], v[116:117], v[202:203]
	v_cvt_pk_bf16_f32 v186, v116, v117
	v_pk_add_f32 v[202:203], v[118:119], v[202:203]
	v_cvt_pk_bf16_f32 v187, v118, v119
	v_pk_add_f32 v[202:203], v[120:121], v[202:203]
	v_cvt_pk_bf16_f32 v188, v120, v121
	v_pk_add_f32 v[202:203], v[122:123], v[202:203]
	v_cvt_pk_bf16_f32 v189, v122, v123
	v_pk_add_f32 v[202:203], v[124:125], v[202:203]
	v_cvt_pk_bf16_f32 v190, v124, v125
	v_pk_add_f32 v[202:203], v[126:127], v[202:203]
	v_cvt_pk_bf16_f32 v191, v126, v127
	s_add_i32 s2, s2, 1
	s_cmp_lg_u32 s2, 44
	s_cbranch_scc1 .Lat_loop
	v_mfma_f32_32x32x16_bf16 v[32:47], v[226:229], v[184:187], v[32:47]
	v_mfma_f32_32x32x16_bf16 v[0:15], v[234:237], v[184:187], v[0:15]
	v_mfma_f32_32x32x16_bf16 v[32:47], v[230:233], v[188:191], v[32:47]
	v_mfma_f32_32x32x16_bf16 v[0:15], v[238:241], v[188:191], v[0:15]
	s_waitcnt lgkmcnt(0)
	v_add_f32_e32 v158, v200, v201
	v_add_f32_e32 v159, v202, v203
	s_branch .LBB0_604

.LBB0_1012:
	ds_read_b64 v[0:1], v129 offset:232
	s_movk_i32 s0, 0x400
	v_cmp_gt_i32_e32 vcc, s0, v64
	s_mov_b64 s[0:1], 0x3195000
	s_waitcnt lgkmcnt(2)
	v_lshlrev_b32_e32 v2, 3, v64
	s_waitcnt lgkmcnt(0)
	v_lshl_add_u64 v[0:1], v[0:1], 0, s[0:1]
	v_ashrrev_i32_e32 v2, 4, v64
	v_and_b32_e32 v3, 15, v64
	v_lshlrev_b32_e32 v128, 4, v3
	v_add_u32_e32 v4, s6, v2
	v_mad_i64_i32 v[6:7], s[2:3], v4, s86, v[0:1]
	v_lshl_add_u64 v[6:7], v[6:7], 0, v[128:129]
	global_load_dwordx4 v[12:15], v[6:7], off
	global_load_dwordx4 v[16:19], v[6:7], off offset:256
	v_add_co_u32_e32 v8, vcc, 0x32000, v6
	s_nop 1
	v_addc_co_u32_e32 v9, vcc, 0, v7, vcc
	global_load_dwordx4 v[20:23], v[8:9], off
	global_load_dwordx4 v[24:27], v[8:9], off offset:256
	v_mul_lo_u32 v5, v2, s92
	v_add3_u32 v5, s57, v5, v128
	v_ashrrev_i32_e32 v10, 5, v64
	v_and_b32_e32 v11, 31, v64
	v_lshlrev_b32_e32 v128, 4, v11
	v_add_u32_e32 v4, s6, v10
	v_mad_i64_i32 v[6:7], s[2:3], v4, s86, v[0:1]
	v_lshl_add_u64 v[6:7], v[6:7], 0, v[128:129]
	global_load_dwordx4 v[28:31], v[6:7], off offset:512
	v_add_co_u32_e32 v6, vcc, 0x19000, v6
	s_nop 1
	v_addc_co_u32_e32 v7, vcc, 0, v7, vcc
	global_load_dwordx4 v[32:35], v[6:7], off offset:512
	v_add_co_u32_e32 v6, vcc, 0x19000, v6
	s_nop 1
	v_addc_co_u32_e32 v7, vcc, 0, v7, vcc
	global_load_dwordx4 v[36:39], v[6:7], off offset:512
	v_add_co_u32_e32 v6, vcc, 0x19000, v6
	s_nop 1
	v_addc_co_u32_e32 v7, vcc, 0, v7, vcc
	global_load_dwordx4 v[40:43], v[6:7], off offset:512
	v_lshlrev_b32_e32 v10, 9, v10
	v_add3_u32 v10, s57, v10, v128
	s_waitcnt vmcnt(7)
	ds_write_b128 v5, v[12:15]
	s_waitcnt vmcnt(6)
	ds_write_b128 v5, v[16:19] offset:17408
	s_waitcnt vmcnt(5)
	ds_write_b128 v5, v[20:23] offset:8704
	s_waitcnt vmcnt(4)
	ds_write_b128 v5, v[24:27] offset:26112
	s_waitcnt vmcnt(3)
	ds_write_b128 v10, v[28:31] offset:34816
	s_waitcnt vmcnt(2)
	ds_write_b128 v10, v[32:35] offset:43008
	s_waitcnt vmcnt(1)
	ds_write_b128 v10, v[36:39] offset:51200
	s_waitcnt vmcnt(0)
	ds_write_b128 v10, v[40:43] offset:59392
	v_ashrrev_i32_e32 v4, 3, v64
	v_and_b32_e32 v2, 7, v64
	v_add_u32_e32 v3, s6, v4
	v_mad_i64_i32 v[0:1], s[0:1], v3, s86, v[0:1]
	v_lshlrev_b32_e32 v128, 3, v2
	v_lshl_add_u64 v[0:1], v[0:1], 0, v[128:129]
	global_load_dwordx2 v[2:3], v[0:1], off offset:1024
	v_lshlrev_b32_e32 v0, 4, v64
	v_and_b32_e32 v1, 64, v0
	v_add_lshl_u32 v1, v1, v4, 6
	v_and_b32_e32 v0, 48, v0
	v_readlane_b32 s0, v255, 16
	v_and_b32_e32 v6, 0x7f, v64
	v_ashrrev_i32_e32 v14, 7, v64
	v_add3_u32 v4, s0, v1, v0
	v_or_b32_e32 v128, s27, v6
	v_mov_b32_e32 v5, v129
	s_movk_i32 s0, 0x204
	v_cmp_gt_i32_e64 s[2:3], 64, v14
	v_mul_lo_u32 v18, v14, s0
	v_lshlrev_b32_e32 v15, 2, v6
	v_add_u32_e32 v16, -4, v14
	v_lshlrev_b32_e32 v17, 6, v14
	s_waitcnt vmcnt(0)
	v_lshlrev_b32_e32 v0, 16, v2
	v_and_b32_e32 v1, 0xffff0000, v2
	v_lshlrev_b32_e32 v2, 16, v3
	v_and_b32_e32 v3, 0xffff0000, v3
	ds_write_b128 v4, v[0:3]
	s_waitcnt lgkmcnt(0)
	s_barrier
	ds_read2_b64 v[0:3], v129 offset0:9 offset1:10
	v_or_b32_e32 v4, s48, v6
	s_waitcnt lgkmcnt(0)
	v_lshl_add_u64 v[0:1], v[128:129], 2, v[0:1]
	v_lshl_add_u64 v[2:3], v[4:5], 2, v[2:3]
	s_and_saveexec_b64 s[6:7], s[2:3]
	s_cbranch_execz .LBB0_1021
	v_add_co_u32_e32 v26, vcc, 0x1000, v0
	global_load_dword v19, v[0:1], off
	global_load_dword v20, v[0:1], off offset:512
	global_load_dword v21, v[0:1], off offset:1024
	global_load_dword v22, v[0:1], off offset:1536
	global_load_dword v23, v[0:1], off offset:2048
	global_load_dword v24, v[0:1], off offset:2560
	global_load_dword v4, v[0:1], off offset:3072
	global_load_dword v5, v[0:1], off offset:3584
	v_addc_co_u32_e32 v27, vcc, 0, v1, vcc
	global_load_dword v6, v[26:27], off
	global_load_dword v7, v[26:27], off offset:512
	global_load_dword v8, v[26:27], off offset:1024
	global_load_dword v9, v[26:27], off offset:1536
	global_load_dword v10, v[26:27], off offset:2048
	global_load_dword v11, v[26:27], off offset:2560
	global_load_dword v12, v[26:27], off offset:3072
	global_load_dword v13, v[26:27], off offset:3584
	global_load_dword v25, v[2:3], off
	v_add_u32_e32 v26, -4, v14
	v_add3_u32 v27, v18, v15, s52
	v_lshlrev_b32_e32 v28, 6, v14
	s_mov_b64 s[20:21], 0

.LBB0_1224:
	s_and_b64 vcc, exec, s[0:1]
	s_cbranch_vccz .LBB0_1215
	s_lshl_b32 s8, s17, 8
	v_add_u32_e32 v0, s8, v200
	v_ashrrev_i32_e32 v1, 31, v0
	s_lshl_b32 s9, s18, 7
	v_lshlrev_b64 v[0:1], 11, v[0:1]
	v_lshl_add_u64 v[182:183], v[178:179], 0, v[0:1]
	v_add_u32_e32 v0, s9, v200
	v_ashrrev_i32_e32 v1, 31, v0
	v_lshlrev_b64 v[0:1], 11, v[0:1]
	v_lshl_add_u64 v[184:185], v[180:181], 0, v[0:1]
	v_add_co_u32_e32 v0, vcc, 0x20000, v182
	s_mov_b64 s[4:5], 0x40000
	s_nop 0
	v_addc_co_u32_e32 v1, vcc, 0, v183, vcc
	v_add_co_u32_e32 v2, vcc, 0x40000, v182
	s_mov_b64 s[0:1], 0x20000
	s_nop 0
	v_addc_co_u32_e32 v3, vcc, 0, v183, vcc
	global_load_dwordx4 v[112:115], v[0:1], off
	global_load_dwordx4 v[116:119], v[2:3], off
	v_add_co_u32_e32 v0, vcc, 0x60000, v182
	global_load_dwordx4 v[120:123], v[182:183], off
	global_load_dwordx4 v[124:127], v[184:185], off
	v_addc_co_u32_e32 v1, vcc, 0, v183, vcc
	v_add_co_u32_e32 v2, vcc, 0x20000, v184
	v_lshl_add_u64 v[188:189], v[182:183], 0, s[4:5]
	s_nop 0
	v_addc_co_u32_e32 v3, vcc, 0, v185, vcc
	global_load_dwordx4 v[130:133], v[0:1], off
	global_load_dwordx4 v[134:137], v[2:3], off
	s_mov_b64 s[4:5], 0x60000
	v_lshl_add_u64 v[186:187], v[182:183], 0, s[0:1]
	v_lshl_add_u64 v[190:191], v[182:183], 0, s[4:5]
	v_lshl_add_u64 v[192:193], v[184:185], 0, s[0:1]
	s_and_saveexec_b64 s[0:1], s[2:3]
	s_xor_b64 s[0:1], exec, s[0:1]
	s_cbranch_execz .LBB0_1231
	v_add_co_u32_e32 v0, vcc, 0x20000, v182
	s_mov_b32 s6, 0
	s_nop 0
	v_addc_co_u32_e32 v1, vcc, 0, v183, vcc
	v_add_co_u32_e32 v2, vcc, 0x40000, v182
	s_nop 1
	v_addc_co_u32_e32 v3, vcc, 0, v183, vcc
	v_add_co_u32_e32 v4, vcc, 0x60000, v182
	s_nop 1
	v_addc_co_u32_e32 v5, vcc, 0, v183, vcc
	v_add_co_u32_e32 v6, vcc, s58, v184
	s_nop 1
	v_addc_co_u32_e32 v7, vcc, 0, v185, vcc
	global_load_dwordx4 v[64:67], v[182:183], off offset:128
	global_load_dwordx4 v[68:71], v[0:1], off offset:128
	global_load_dwordx4 v[80:83], v[2:3], off offset:128
	global_load_dwordx4 v[84:87], v[4:5], off offset:128
	global_load_dwordx4 v[96:99], v[184:185], off offset:128
	global_load_dwordx4 v[100:103], v[6:7], off offset:128
	global_load_dwordx4 v[72:75], v[182:183], off offset:256
	global_load_dwordx4 v[76:79], v[0:1], off offset:256
	global_load_dwordx4 v[88:91], v[2:3], off offset:256
	global_load_dwordx4 v[92:95], v[4:5], off offset:256
	global_load_dwordx4 v[104:107], v[184:185], off offset:256
	global_load_dwordx4 v[108:111], v[6:7], off offset:256
	v_mov_b32_e32 v0, 0
	v_mov_b32_e32 v1, v0
	v_mov_b32_e32 v2, v0
	v_mov_b32_e32 v3, v0
	v_mov_b32_e32 v4, v0
	v_mov_b32_e32 v5, v0
	v_mov_b32_e32 v6, v0
	v_mov_b32_e32 v7, v0
	v_mov_b32_e32 v8, v0
	v_mov_b32_e32 v9, v0
	v_mov_b32_e32 v10, v0
	v_mov_b32_e32 v11, v0
	v_mov_b32_e32 v12, v0
	v_mov_b32_e32 v13, v0
	v_mov_b32_e32 v14, v0
	v_mov_b32_e32 v15, v0
	v_mov_b32_e32 v16, v0
	v_mov_b32_e32 v17, v0
	v_mov_b32_e32 v18, v0
	v_mov_b32_e32 v19, v0
	v_mov_b32_e32 v20, v0
	v_mov_b32_e32 v21, v0
	v_mov_b32_e32 v22, v0
	v_mov_b32_e32 v23, v0
	v_mov_b32_e32 v24, v0
	v_mov_b32_e32 v25, v0
	v_mov_b32_e32 v26, v0
	v_mov_b32_e32 v27, v0
	v_mov_b32_e32 v28, v0
	v_mov_b32_e32 v29, v0
	v_mov_b32_e32 v30, v0
	v_mov_b32_e32 v31, v0
	v_mov_b32_e32 v32, v0
	v_mov_b32_e32 v33, v0
	v_mov_b32_e32 v34, v0
	v_mov_b32_e32 v35, v0
	v_mov_b32_e32 v36, v0
	v_mov_b32_e32 v37, v0
	v_mov_b32_e32 v38, v0
	v_mov_b32_e32 v39, v0
	v_mov_b32_e32 v40, v0
	v_mov_b32_e32 v41, v0
	v_mov_b32_e32 v42, v0
	v_mov_b32_e32 v43, v0
	v_mov_b32_e32 v44, v0
	v_mov_b32_e32 v45, v0
	v_mov_b32_e32 v46, v0
	v_mov_b32_e32 v47, v0
	v_mov_b32_e32 v48, v0
	v_mov_b32_e32 v49, v0
	v_mov_b32_e32 v50, v0
	v_mov_b32_e32 v51, v0
	v_mov_b32_e32 v52, v0
	v_mov_b32_e32 v53, v0
	v_mov_b32_e32 v54, v0
	v_mov_b32_e32 v55, v0
	v_mov_b32_e32 v56, v0
	v_mov_b32_e32 v57, v0
	v_mov_b32_e32 v58, v0
	v_mov_b32_e32 v59, v0
	v_mov_b32_e32 v60, v0
	v_mov_b32_e32 v61, v0
	v_mov_b32_e32 v62, v0
	v_mov_b32_e32 v63, v0
	s_waitcnt vmcnt(15)
	ds_write_b128 v201, v[120:123]
	ds_write_b128 v201, v[112:115] offset:9216
	ds_write_b128 v201, v[116:119] offset:18432
	s_waitcnt vmcnt(13)
	ds_write_b128 v201, v[130:133] offset:27648
	ds_write_b128 v201, v[124:127] offset:36864
	s_waitcnt vmcnt(12)
	ds_write_b128 v201, v[134:137] offset:46080
	s_waitcnt lgkmcnt(0)
	s_barrier
	s_branch .LBB0_1228
.LBB0_1227:
	s_min_u32 s7, s6, 11
	s_lshl_b32 s48, s7, 7
	s_add_i32 s20, s48, 0x200
	s_mov_b32 s21, s49
	s_waitcnt vmcnt(6)
	v_lshl_add_u64 v[72:73], v[182:183], 0, s[48:49]
	v_lshl_add_u64 v[76:77], v[186:187], 0, s[20:21]
	v_lshl_add_u64 v[88:89], v[188:189], 0, s[20:21]
	v_lshl_add_u64 v[92:93], v[190:191], 0, s[20:21]
	v_lshl_add_u64 v[104:105], v[184:185], 0, s[48:49]
	v_lshl_add_u64 v[108:109], v[192:193], 0, s[20:21]
	global_load_dwordx4 v[72:75], v[72:73], off offset:512
	s_nop 0
	global_load_dwordx4 v[76:79], v[76:77], off
	s_nop 0
	global_load_dwordx4 v[88:91], v[88:89], off
	s_nop 0
	global_load_dwordx4 v[92:95], v[92:93], off
	s_nop 0
	global_load_dwordx4 v[104:107], v[104:105], off offset:512
	s_nop 0
	global_load_dwordx4 v[108:111], v[108:109], off
	s_add_i32 s6, s6, 2
	s_waitcnt lgkmcnt(0)
	s_barrier
	v_mfma_f32_32x32x16_bf16 v[48:63], v[162:165], v[170:173], v[48:63]
	v_mfma_f32_32x32x16_bf16 v[32:47], v[162:165], v[174:177], v[32:47]
	v_mfma_f32_32x32x16_bf16 v[16:31], v[166:169], v[170:173], v[16:31]
	v_mfma_f32_32x32x16_bf16 v[0:15], v[166:169], v[174:177], v[0:15]
	v_mfma_f32_32x32x16_bf16 v[48:63], v[130:133], v[134:137], v[48:63]
	v_mfma_f32_32x32x16_bf16 v[32:47], v[130:133], v[150:153], v[32:47]
	v_mfma_f32_32x32x16_bf16 v[16:31], v[142:145], v[134:137], v[16:31]
	v_mfma_f32_32x32x16_bf16 v[0:15], v[142:145], v[150:153], v[0:15]
	v_mfma_f32_32x32x16_bf16 v[48:63], v[138:141], v[154:157], v[48:63]
	v_mfma_f32_32x32x16_bf16 v[32:47], v[138:141], v[158:161], v[32:47]
	v_mfma_f32_32x32x16_bf16 v[16:31], v[146:149], v[154:157], v[16:31]
	v_mfma_f32_32x32x16_bf16 v[0:15], v[146:149], v[158:161], v[0:15]
	v_mfma_f32_32x32x16_bf16 v[48:63], v[116:119], v[120:123], v[48:63]
	v_mfma_f32_32x32x16_bf16 v[32:47], v[116:119], v[124:127], v[32:47]
	v_mfma_f32_32x32x16_bf16 v[16:31], v[112:115], v[120:123], v[16:31]
	v_mfma_f32_32x32x16_bf16 v[0:15], v[112:115], v[124:127], v[0:15]
	s_andn2_b64 vcc, exec, s[4:5]
	s_barrier
	s_cbranch_vccz .LBB0_1230
.LBB0_1228:
	ds_read_b128 v[112:115], v203
	ds_read_b128 v[116:119], v203 offset:32
	ds_read_b128 v[120:123], v203 offset:4608
	ds_read_b128 v[124:127], v203 offset:4640
	ds_read_b128 v[130:133], v204 offset:36864
	ds_read_b128 v[134:137], v204 offset:36896
	ds_read_b128 v[138:141], v204 offset:41472
	ds_read_b128 v[142:145], v204 offset:41504
	ds_read_b128 v[146:149], v203 offset:64
	ds_read_b128 v[150:153], v203 offset:96
	ds_read_b128 v[154:157], v203 offset:4672
	ds_read_b128 v[158:161], v203 offset:4704
	ds_read_b128 v[162:165], v204 offset:36928
	ds_read_b128 v[166:169], v204 offset:36960
	ds_read_b128 v[170:173], v204 offset:41536
	ds_read_b128 v[174:177], v204 offset:41568
	s_min_u32 s4, s6, 12
	s_lshl_b32 s48, s4, 7
	s_add_i32 s4, s48, 0x180
	s_mov_b32 s5, s49
	s_waitcnt vmcnt(11)
	ds_write_b128 v201, v[64:67] offset:55296
	s_waitcnt vmcnt(10)
	ds_write_b128 v201, v[68:71] offset:64512
	s_waitcnt vmcnt(9)
	ds_write_b128 v205, v[80:83] offset:18432
	s_waitcnt vmcnt(8)
	ds_write_b128 v205, v[84:87] offset:27648
	s_waitcnt vmcnt(7)
	ds_write_b128 v234, v[96:99]
	s_waitcnt vmcnt(6)
	ds_write_b128 v234, v[100:103] offset:9216
	v_lshl_add_u64 v[64:65], v[182:183], 0, s[48:49]
	v_lshl_add_u64 v[68:69], v[186:187], 0, s[4:5]
	v_lshl_add_u64 v[80:81], v[188:189], 0, s[4:5]
	v_lshl_add_u64 v[84:85], v[190:191], 0, s[4:5]
	v_lshl_add_u64 v[96:97], v[184:185], 0, s[48:49]
	v_lshl_add_u64 v[100:101], v[192:193], 0, s[4:5]
	global_load_dwordx4 v[64:67], v[64:65], off offset:384
	s_nop 0
	global_load_dwordx4 v[68:71], v[68:69], off
	s_nop 0
	global_load_dwordx4 v[80:83], v[80:81], off
	s_nop 0
	global_load_dwordx4 v[84:87], v[84:85], off
	s_nop 0
	global_load_dwordx4 v[96:99], v[96:97], off offset:384
	s_nop 0
	global_load_dwordx4 v[100:103], v[100:101], off
	s_waitcnt lgkmcnt(0)
	s_barrier
	v_mfma_f32_32x32x16_bf16 v[48:63], v[112:115], v[130:133], v[48:63]
	v_mfma_f32_32x32x16_bf16 v[32:47], v[112:115], v[138:141], v[32:47]
	v_mfma_f32_32x32x16_bf16 v[16:31], v[120:123], v[130:133], v[16:31]
	v_mfma_f32_32x32x16_bf16 v[0:15], v[120:123], v[138:141], v[0:15]
	v_mfma_f32_32x32x16_bf16 v[48:63], v[116:119], v[134:137], v[48:63]
	v_mfma_f32_32x32x16_bf16 v[32:47], v[116:119], v[142:145], v[32:47]
	v_mfma_f32_32x32x16_bf16 v[16:31], v[124:127], v[134:137], v[16:31]
	v_mfma_f32_32x32x16_bf16 v[0:15], v[124:127], v[142:145], v[0:15]
	v_mfma_f32_32x32x16_bf16 v[48:63], v[146:149], v[162:165], v[48:63]
	v_mfma_f32_32x32x16_bf16 v[32:47], v[146:149], v[170:173], v[32:47]
	v_mfma_f32_32x32x16_bf16 v[16:31], v[154:157], v[162:165], v[16:31]
	v_mfma_f32_32x32x16_bf16 v[0:15], v[154:157], v[170:173], v[0:15]
	v_mfma_f32_32x32x16_bf16 v[48:63], v[150:153], v[166:169], v[48:63]
	v_mfma_f32_32x32x16_bf16 v[32:47], v[150:153], v[174:177], v[32:47]
	v_mfma_f32_32x32x16_bf16 v[16:31], v[158:161], v[166:169], v[16:31]
	v_mfma_f32_32x32x16_bf16 v[0:15], v[158:161], v[174:177], v[0:15]
	s_barrier
	ds_read_b128 v[162:165], v203 offset:55296
	ds_read_b128 v[130:133], v203 offset:55328
	ds_read_b128 v[170:173], v235
	ds_read_b128 v[134:137], v235 offset:32
	ds_read_b128 v[166:169], v203 offset:59904
	ds_read_b128 v[142:145], v203 offset:59936
	ds_read_b128 v[174:177], v235 offset:4608
	ds_read_b128 v[150:153], v235 offset:4640
	ds_read_b128 v[138:141], v203 offset:55360
	ds_read_b128 v[116:119], v203 offset:55392
	ds_read_b128 v[146:149], v203 offset:59968
	ds_read_b128 v[112:115], v203 offset:60000
	ds_read_b128 v[154:157], v235 offset:64
	ds_read_b128 v[120:123], v235 offset:96
	ds_read_b128 v[158:161], v235 offset:4672
	ds_read_b128 v[124:127], v235 offset:4704
	s_cmp_gt_u32 s6, 13
	s_cselect_b64 s[4:5], -1, 0
	s_and_b64 vcc, exec, s[4:5]
	s_cbranch_vccnz .LBB0_1227
	s_waitcnt vmcnt(11)
	ds_write_b128 v201, v[72:75]
	s_waitcnt vmcnt(10)
	ds_write_b128 v201, v[76:79] offset:9216
	s_waitcnt vmcnt(9)
	ds_write_b128 v201, v[88:91] offset:18432
	s_waitcnt vmcnt(8)
	ds_write_b128 v201, v[92:95] offset:27648
	s_waitcnt vmcnt(7)
	ds_write_b128 v201, v[104:107] offset:36864
	s_waitcnt vmcnt(6)
	ds_write_b128 v201, v[108:111] offset:46080
	s_branch .LBB0_1227
.LBB0_1230:
.LBB0_1231:
	s_andn2_saveexec_b64 s[0:1], s[0:1]
	s_cbranch_execz .LBB0_1240
	s_nop 5
	v_add_co_u32_e32 v24, vcc, 0x20000, v182
	global_load_dwordx4 v[0:3], v[182:183], off offset:128
	s_nop 0
	v_addc_co_u32_e32 v25, vcc, 0, v183, vcc
	v_add_co_u32_e32 v26, vcc, 0x40000, v182
	global_load_dwordx4 v[4:7], v[24:25], off offset:128
	s_nop 0
	v_addc_co_u32_e32 v27, vcc, 0, v183, vcc
	v_add_co_u32_e32 v28, vcc, 0x60000, v182
	global_load_dwordx4 v[8:11], v[26:27], off offset:128
	s_nop 0
	v_addc_co_u32_e32 v29, vcc, 0, v183, vcc
	global_load_dwordx4 v[12:15], v[28:29], off offset:128
	global_load_dwordx4 v[16:19], v[184:185], off offset:128
	v_add_co_u32_e32 v30, vcc, s58, v184
	s_mov_b32 s19, 0
	s_nop 0
	v_addc_co_u32_e32 v31, vcc, 0, v185, vcc
	global_load_dwordx4 v[20:23], v[30:31], off offset:128
	global_load_dwordx4 v[64:67], v[182:183], off offset:256
	global_load_dwordx4 v[68:71], v[24:25], off offset:256
	global_load_dwordx4 v[72:75], v[28:29], off offset:256
	global_load_dwordx4 v[84:87], v[26:27], off offset:256
	global_load_dwordx4 v[96:99], v[184:185], off offset:256
	global_load_dwordx4 v[100:103], v[30:31], off offset:256
	global_load_dwordx4 v[76:79], v[182:183], off offset:384
	global_load_dwordx4 v[80:83], v[24:25], off offset:384
	global_load_dwordx4 v[88:91], v[26:27], off offset:384
	global_load_dwordx4 v[92:95], v[28:29], off offset:384
	global_load_dwordx4 v[104:107], v[184:185], off offset:384
	global_load_dwordx4 v[108:111], v[30:31], off offset:384
	s_waitcnt vmcnt(21)
	ds_write_b128 v201, v[120:123]
	ds_write_b128 v201, v[112:115] offset:9216
	ds_write_b128 v201, v[116:119] offset:18432
	s_waitcnt vmcnt(19)
	ds_write_b128 v201, v[130:133] offset:27648
	ds_write_b128 v201, v[124:127] offset:36864
	s_waitcnt vmcnt(18)
	ds_write_b128 v201, v[134:137] offset:46080
	s_waitcnt vmcnt(17)
	ds_write_b128 v201, v[0:3] offset:55296
	s_waitcnt vmcnt(13)
	ds_write_b128 v234, v[16:19]
	ds_write_b128 v201, v[4:7] offset:64512
	ds_write_b128 v205, v[8:11] offset:18432
	ds_write_b128 v205, v[12:15] offset:27648
	s_waitcnt vmcnt(12)
	ds_write_b128 v234, v[20:23] offset:9216
	s_waitcnt lgkmcnt(0)
	s_barrier
	ds_read_b128 v[116:119], v203
	ds_read_b128 v[112:115], v203 offset:32
	ds_read_b128 v[124:127], v204 offset:36864
	ds_read_b128 v[120:123], v204 offset:36896
	ds_read_b128 v[134:137], v203 offset:4608
	ds_read_b128 v[130:133], v203 offset:4640
	ds_read_b128 v[154:157], v204 offset:41472
	ds_read_b128 v[142:145], v204 offset:41504
	ds_read_b128 v[138:141], v203 offset:64
	ds_read_b128 v[146:149], v203 offset:96
	ds_read_b128 v[158:161], v203 offset:4672
	ds_read_b128 v[150:153], v203 offset:4704
	ds_read_b128 v[170:173], v204 offset:36928
	ds_read_b128 v[162:165], v204 offset:36960
	ds_read_b128 v[174:177], v204 offset:41536
	ds_read_b128 v[166:169], v204 offset:41568
	v_mov_b32_e32 v0, 0
	v_mov_b32_e32 v1, v0
	v_mov_b32_e32 v2, v0
	v_mov_b32_e32 v3, v0
	v_mov_b32_e32 v4, v0
	v_mov_b32_e32 v5, v0
	v_mov_b32_e32 v6, v0
	v_mov_b32_e32 v7, v0
	v_mov_b32_e32 v8, v0
	v_mov_b32_e32 v9, v0
	v_mov_b32_e32 v10, v0
	v_mov_b32_e32 v11, v0
	v_mov_b32_e32 v12, v0
	v_mov_b32_e32 v13, v0
	v_mov_b32_e32 v14, v0
	v_mov_b32_e32 v15, v0
	v_mov_b32_e32 v16, v0
	v_mov_b32_e32 v17, v0
	v_mov_b32_e32 v18, v0
	v_mov_b32_e32 v19, v0
	v_mov_b32_e32 v20, v0
	v_mov_b32_e32 v21, v0
	v_mov_b32_e32 v22, v0
	v_mov_b32_e32 v23, v0
	v_mov_b32_e32 v24, v0
	v_mov_b32_e32 v25, v0
	v_mov_b32_e32 v26, v0
	v_mov_b32_e32 v27, v0
	v_mov_b32_e32 v28, v0
	v_mov_b32_e32 v29, v0
	v_mov_b32_e32 v30, v0
	v_mov_b32_e32 v31, v0
	v_mov_b32_e32 v32, v0
	v_mov_b32_e32 v33, v0
	v_mov_b32_e32 v34, v0
	v_mov_b32_e32 v35, v0
	v_mov_b32_e32 v36, v0
	v_mov_b32_e32 v37, v0
	v_mov_b32_e32 v38, v0
	v_mov_b32_e32 v39, v0
	v_mov_b32_e32 v40, v0
	v_mov_b32_e32 v41, v0
	v_mov_b32_e32 v42, v0
	v_mov_b32_e32 v43, v0
	v_mov_b32_e32 v44, v0
	v_mov_b32_e32 v45, v0
	v_mov_b32_e32 v46, v0
	v_mov_b32_e32 v47, v0
	v_mov_b32_e32 v48, v0
	v_mov_b32_e32 v49, v0
	v_mov_b32_e32 v50, v0
	v_mov_b32_e32 v51, v0
	v_mov_b32_e32 v52, v0
	v_mov_b32_e32 v53, v0
	v_mov_b32_e32 v54, v0
	v_mov_b32_e32 v55, v0
	v_mov_b32_e32 v56, v0
	v_mov_b32_e32 v57, v0
	v_mov_b32_e32 v58, v0
	v_mov_b32_e32 v59, v0
	v_mov_b32_e32 v60, v0
	v_mov_b32_e32 v61, v0
	v_mov_b32_e32 v62, v0
	v_mov_b32_e32 v63, v0
	s_branch .LBB0_1234
.LBB0_1233:
	s_min_u32 s6, s19, 10
	s_lshl_b32 s48, s6, 7
	s_add_i32 s6, s48, 0x280
	s_mov_b32 s7, s49
	s_waitcnt vmcnt(6)
	v_lshl_add_u64 v[76:77], v[182:183], 0, s[48:49]
	v_lshl_add_u64 v[80:81], v[186:187], 0, s[6:7]
	v_lshl_add_u64 v[88:89], v[188:189], 0, s[6:7]
	v_lshl_add_u64 v[92:93], v[190:191], 0, s[6:7]
	v_lshl_add_u64 v[104:105], v[184:185], 0, s[48:49]
	v_lshl_add_u64 v[108:109], v[192:193], 0, s[6:7]
	global_load_dwordx4 v[76:79], v[76:77], off offset:640
	s_nop 0
	global_load_dwordx4 v[80:83], v[80:81], off
	s_nop 0
	global_load_dwordx4 v[88:91], v[88:89], off
	s_nop 0
	global_load_dwordx4 v[92:95], v[92:93], off
	s_nop 0
	global_load_dwordx4 v[104:107], v[104:105], off offset:640
	s_nop 0
	global_load_dwordx4 v[108:111], v[108:109], off
	s_add_i32 s19, s19, 2
	s_and_b64 vcc, exec, s[4:5]
	s_waitcnt lgkmcnt(0)
	s_barrier
	s_cbranch_vccnz .LBB0_1240
.LBB0_1234:
	s_waitcnt lgkmcnt(13)
	v_mfma_f32_32x32x16_bf16 v[48:63], v[116:119], v[124:127], v[48:63]
	s_waitcnt lgkmcnt(9)
	v_mfma_f32_32x32x16_bf16 v[32:47], v[116:119], v[154:157], v[32:47]
	v_mfma_f32_32x32x16_bf16 v[16:31], v[134:137], v[124:127], v[16:31]
	v_mfma_f32_32x32x16_bf16 v[0:15], v[134:137], v[154:157], v[0:15]
	v_mfma_f32_32x32x16_bf16 v[48:63], v[112:115], v[120:123], v[48:63]
	s_waitcnt lgkmcnt(8)
	v_mfma_f32_32x32x16_bf16 v[32:47], v[112:115], v[142:145], v[32:47]
	v_mfma_f32_32x32x16_bf16 v[16:31], v[130:133], v[120:123], v[16:31]
	v_mfma_f32_32x32x16_bf16 v[0:15], v[130:133], v[142:145], v[0:15]
	s_waitcnt lgkmcnt(3)
	v_mfma_f32_32x32x16_bf16 v[48:63], v[138:141], v[170:173], v[48:63]
	s_waitcnt lgkmcnt(1)
	v_mfma_f32_32x32x16_bf16 v[32:47], v[138:141], v[174:177], v[32:47]
	v_mfma_f32_32x32x16_bf16 v[16:31], v[158:161], v[170:173], v[16:31]
	v_mfma_f32_32x32x16_bf16 v[0:15], v[158:161], v[174:177], v[0:15]
	v_mfma_f32_32x32x16_bf16 v[48:63], v[146:149], v[162:165], v[48:63]
	s_waitcnt lgkmcnt(0)
	v_mfma_f32_32x32x16_bf16 v[32:47], v[146:149], v[166:169], v[32:47]
	v_mfma_f32_32x32x16_bf16 v[16:31], v[150:153], v[162:165], v[16:31]
	v_mfma_f32_32x32x16_bf16 v[0:15], v[150:153], v[166:169], v[0:15]
	s_barrier
	ds_read_b128 v[116:119], v203 offset:55296
	ds_read_b128 v[112:115], v203 offset:55328
	ds_read_b128 v[124:127], v235
	ds_read_b128 v[120:123], v235 offset:32
	ds_read_b128 v[134:137], v203 offset:59904
	ds_read_b128 v[130:133], v203 offset:59936
	ds_read_b128 v[154:157], v235 offset:4608
	ds_read_b128 v[142:145], v235 offset:4640
	ds_read_b128 v[138:141], v203 offset:55360
	ds_read_b128 v[146:149], v203 offset:55392
	ds_read_b128 v[158:161], v203 offset:59968
	ds_read_b128 v[150:153], v203 offset:60000
	ds_read_b128 v[170:173], v235 offset:64
	ds_read_b128 v[162:165], v235 offset:96
	ds_read_b128 v[174:177], v235 offset:4672
	ds_read_b128 v[166:169], v235 offset:4704
	s_cmp_lt_u32 s19, 14
	s_cselect_b64 s[6:7], -1, 0
	s_cmp_gt_u32 s19, 13
	s_cselect_b64 s[4:5], -1, 0
	s_and_b64 vcc, exec, s[4:5]
	s_cbranch_vccnz .LBB0_1236
	s_waitcnt vmcnt(11)
	ds_write_b128 v201, v[64:67]
	s_waitcnt vmcnt(10)
	ds_write_b128 v201, v[68:71] offset:9216
	s_waitcnt vmcnt(8)
	ds_write_b128 v201, v[84:87] offset:18432
	ds_write_b128 v201, v[72:75] offset:27648
	s_waitcnt vmcnt(7)
	ds_write_b128 v201, v[96:99] offset:36864
	s_waitcnt vmcnt(6)
	ds_write_b128 v201, v[100:103] offset:46080
.LBB0_1236:
	s_min_u32 s20, s19, 11
	s_lshl_b32 s48, s20, 7
	s_add_i32 s20, s48, 0x200
	s_mov_b32 s21, s49
	s_waitcnt vmcnt(6)
	v_lshl_add_u64 v[64:65], v[182:183], 0, s[48:49]
	v_lshl_add_u64 v[68:69], v[186:187], 0, s[20:21]
	v_lshl_add_u64 v[72:73], v[188:189], 0, s[20:21]
	v_lshl_add_u64 v[74:75], v[190:191], 0, s[20:21]
	v_lshl_add_u64 v[96:97], v[184:185], 0, s[48:49]
	v_lshl_add_u64 v[100:101], v[192:193], 0, s[20:21]
	global_load_dwordx4 v[64:67], v[64:65], off offset:512
	s_nop 0
	global_load_dwordx4 v[68:71], v[68:69], off
	s_nop 0
	global_load_dwordx4 v[84:87], v[72:73], off
	s_nop 0
	global_load_dwordx4 v[72:75], v[74:75], off
	s_nop 0
	global_load_dwordx4 v[96:99], v[96:97], off offset:512
	s_nop 0
	global_load_dwordx4 v[100:103], v[100:101], off
	s_waitcnt lgkmcnt(0)
	s_barrier
	v_mfma_f32_32x32x16_bf16 v[48:63], v[116:119], v[124:127], v[48:63]
	v_mfma_f32_32x32x16_bf16 v[32:47], v[116:119], v[154:157], v[32:47]
	v_mfma_f32_32x32x16_bf16 v[16:31], v[134:137], v[124:127], v[16:31]
	v_mfma_f32_32x32x16_bf16 v[0:15], v[134:137], v[154:157], v[0:15]
	v_mfma_f32_32x32x16_bf16 v[48:63], v[112:115], v[120:123], v[48:63]
	v_mfma_f32_32x32x16_bf16 v[32:47], v[112:115], v[142:145], v[32:47]
	v_mfma_f32_32x32x16_bf16 v[16:31], v[130:133], v[120:123], v[16:31]
	v_mfma_f32_32x32x16_bf16 v[0:15], v[130:133], v[142:145], v[0:15]
	v_mfma_f32_32x32x16_bf16 v[48:63], v[138:141], v[170:173], v[48:63]
	v_mfma_f32_32x32x16_bf16 v[32:47], v[138:141], v[174:177], v[32:47]
	v_mfma_f32_32x32x16_bf16 v[16:31], v[158:161], v[170:173], v[16:31]
	v_mfma_f32_32x32x16_bf16 v[0:15], v[158:161], v[174:177], v[0:15]
	v_mfma_f32_32x32x16_bf16 v[48:63], v[146:149], v[162:165], v[48:63]
	v_mfma_f32_32x32x16_bf16 v[32:47], v[146:149], v[166:169], v[32:47]
	v_mfma_f32_32x32x16_bf16 v[16:31], v[150:153], v[162:165], v[16:31]
	v_mfma_f32_32x32x16_bf16 v[0:15], v[150:153], v[166:169], v[0:15]
	s_andn2_b64 vcc, exec, s[6:7]
	s_barrier
	s_cbranch_vccnz .LBB0_1238
	ds_read_b128 v[116:119], v203
	ds_read_b128 v[112:115], v203 offset:32
	ds_read_b128 v[124:127], v204 offset:36864
	ds_read_b128 v[120:123], v204 offset:36896
	ds_read_b128 v[134:137], v203 offset:4608
	ds_read_b128 v[130:133], v203 offset:4640
	ds_read_b128 v[154:157], v204 offset:41472
	ds_read_b128 v[142:145], v204 offset:41504
	ds_read_b128 v[138:141], v203 offset:64
	ds_read_b128 v[146:149], v203 offset:96
	ds_read_b128 v[158:161], v203 offset:4672
	ds_read_b128 v[150:153], v203 offset:4704
	ds_read_b128 v[170:173], v204 offset:36928
	ds_read_b128 v[162:165], v204 offset:36960
	ds_read_b128 v[174:177], v204 offset:41536
	ds_read_b128 v[166:169], v204 offset:41568
.LBB0_1238:
	s_cmp_gt_u32 s19, 12
	s_cbranch_scc1 .LBB0_1233
	s_waitcnt vmcnt(11)
	ds_write_b128 v201, v[76:79] offset:55296
	s_waitcnt vmcnt(10)
	ds_write_b128 v201, v[80:83] offset:64512
	s_waitcnt vmcnt(9)
	ds_write_b128 v205, v[88:91] offset:18432
	s_waitcnt vmcnt(8)
	ds_write_b128 v205, v[92:95] offset:27648
	s_waitcnt vmcnt(7)
	ds_write_b128 v234, v[104:107]
	s_waitcnt vmcnt(6)
	ds_write_b128 v234, v[108:111] offset:9216
	s_branch .LBB0_1233
